# adds: GEMM K-loop load segments run at priority 2 (above the MMA segments' priority 1)
# speedup vs baseline: 1.0076x; 1.0018x over previous
; #define PG8_STAGE(bufoff, gbase, voff) do { _Pragma("unroll") for (int _i = 0; _i < 2; ++_i) \
;         __builtin_amdgcn_global_load_lds((const unsigned*)((const char*)(gbase) + (voff)[_i]), (PG8_LAS unsigned*)(lds + (bufoff) + ldsw + _i * 8192), 16, 0, 0); } while (0)
; #define PG8_LDA(dst, b, h) do { _Pragma("unroll") for (int m = 0; m < 4; ++m) _Pragma("unroll") for (int k = 0; k < 2; ++k) dst[m][k] = *(const PG8_LAS bf16x8*)(lds + PG8_SA(b, h) + aoff + m * 2048 + k * 1024); } while (0)
; #define PG8_LDB(dst, b, h) do { _Pragma("unroll") for (int n = 0; n < 2; ++n) _Pragma("unroll") for (int k = 0; k < 2; ++k) dst[n][k] = *(const PG8_LAS bf16x8*)(lds + PG8_SB(b, h) + boff + n * 2048 + k * 1024); } while (0)
; #define PG8_MMA(ai, bj, At, Bt) do { __builtin_amdgcn_s_setprio(1); _Pragma("unroll") for (int m = 0; m < 4; ++m) _Pragma("unroll") for (int n = 0; n < 2; ++n) _Pragma("unroll") for (int k = 0; k < 2; ++k) \
;         acc[ai][bj][m][n] = __builtin_amdgcn_mfma_f32_16x16x32_bf16(Bt[n][k], At[m][k], acc[ai][bj][m][n], 0, 0, 0); __builtin_amdgcn_s_setprio(0); } while (0)
; #define PG8_WAIT_V(n) asm volatile("s_waitcnt vmcnt(" #n ")" ::: "memory")
; #define PG8_WAIT_L(n) asm volatile("s_waitcnt lgkmcnt(" #n ")" ::: "memory")
; #define PG8_BAR __builtin_amdgcn_s_barrier()
; #define PG8_SCHED __builtin_amdgcn_sched_barrier(0)
; template <class Epi, class Sched, bool ALIGN_EPI = false, bool SP2 = false>
; __device__ __forceinline__ void gemm_phase(PG8_LAS unsigned char* lds, const Gemm g, const Sched& S, const Epi& E) {
;     ...
;             PG8_LDB(B0, 0, 0); PG8_LDB(B1, 0, 1); PG8_SCHED; PG8_LDA(At, 0, 0); PG8_STAGE(PG8_SA(1, 1), a1 + hstep, voffA);
;             PG8_WAIT_V(8); PG8_WAIT_L(0); PG8_BAR; PG8_MMA(0, 0, At, B0); PG8_MMA(0, 1, At, B1); PG8_BAR; PG8_SCHED;
;             PG8_LDA(At, 0, 1); PG8_STAGE(PG8_SB(0, 0), b2, voffB); PG8_STAGE(PG8_SB(0, 1), b2 + hstep, voffB); PG8_STAGE(PG8_SA(0, 0), a2, voffA);
.Lpeel_p1:
	s_add_u32 s40, s22, 0xfffc0080
	s_addc_u32 s41, s23, -1
	s_add_i32 s55, 0, 0x10000
	s_cmp_eq_u32 s49, 12
	s_cselect_b32 s61, s5, s41
	s_cselect_b32 s60, s7, s40
	s_cselect_b32 s41, s34, s47
	s_cselect_b32 s40, s35, s45
	s_add_i32 s57, 0, 0x14000
	v_add_u32_e32 v90, s55, v233
	v_add_u32_e32 v110, s57, v233
	ds_read_b128 v[74:77], v90
	ds_read_b128 v[78:81], v90 offset:1024
	ds_read_b128 v[82:85], v90 offset:2048
	ds_read_b128 v[90:93], v90 offset:3072
	ds_read_b128 v[94:97], v110
	ds_read_b128 v[98:101], v110 offset:1024
	ds_read_b128 v[102:105], v110 offset:2048
	ds_read_b128 v[110:113], v110 offset:3072
	v_lshl_add_u64 v[216:217], s[22:23], 0, v[188:189]
	s_add_i32 m0, s66, 0xc000
	ds_read_b128 v[162:165], v234
	ds_read_b128 v[166:169], v234 offset:1024
	ds_read_b128 v[192:195], v234 offset:2048
	ds_read_b128 v[196:199], v234 offset:3072
	ds_read_b128 v[200:203], v234 offset:4096
	ds_read_b128 v[204:207], v234 offset:5120
	ds_read_b128 v[208:211], v234 offset:6144
	ds_read_b128 v[212:215], v234 offset:7168
	v_lshl_add_u64 v[216:217], s[22:23], 0, v[190:191]
	s_add_i32 m0, s66, 0xe000
	s_nop 0
	s_waitcnt lgkmcnt(0)
	s_barrier
	s_setprio 1
	s_waitcnt lgkmcnt(0)
	v_mfma_f32_16x16x32_bf16 v[158:161], v[74:77], v[162:165], v[158:161]
	v_mfma_f32_16x16x32_bf16 v[154:157], v[82:85], v[162:165], v[154:157]
	v_mfma_f32_16x16x32_bf16 v[142:145], v[74:77], v[192:195], v[142:145]
	v_mfma_f32_16x16x32_bf16 v[138:141], v[82:85], v[192:195], v[138:141]
	v_mfma_f32_16x16x32_bf16 v[126:129], v[74:77], v[200:203], v[126:129]
	v_mfma_f32_16x16x32_bf16 v[122:125], v[82:85], v[200:203], v[122:125]
	v_mfma_f32_16x16x32_bf16 v[106:109], v[74:77], v[208:211], v[106:109]
	v_mfma_f32_16x16x32_bf16 v[86:89], v[82:85], v[208:211], v[86:89]
	v_mfma_f32_16x16x32_bf16 v[158:161], v[78:81], v[166:169], v[158:161]
	v_mfma_f32_16x16x32_bf16 v[154:157], v[90:93], v[166:169], v[154:157]
	v_mfma_f32_16x16x32_bf16 v[142:145], v[78:81], v[196:199], v[142:145]
	v_mfma_f32_16x16x32_bf16 v[138:141], v[90:93], v[196:199], v[138:141]
	v_mfma_f32_16x16x32_bf16 v[126:129], v[78:81], v[204:207], v[126:129]
	v_mfma_f32_16x16x32_bf16 v[122:125], v[90:93], v[204:207], v[122:125]
	v_mfma_f32_16x16x32_bf16 v[106:109], v[78:81], v[212:215], v[106:109]
	v_mfma_f32_16x16x32_bf16 v[86:89], v[90:93], v[212:215], v[86:89]
	s_setprio 2
	s_setprio 1
	v_mfma_f32_16x16x32_bf16 v[150:153], v[94:97], v[162:165], v[150:153]
	v_mfma_f32_16x16x32_bf16 v[146:149], v[102:105], v[162:165], v[146:149]
	v_mfma_f32_16x16x32_bf16 v[134:137], v[94:97], v[192:195], v[134:137]
	v_mfma_f32_16x16x32_bf16 v[130:133], v[102:105], v[192:195], v[130:133]
	v_mfma_f32_16x16x32_bf16 v[118:121], v[94:97], v[200:203], v[118:121]
	v_mfma_f32_16x16x32_bf16 v[114:117], v[102:105], v[200:203], v[114:117]
	v_mfma_f32_16x16x32_bf16 v[70:73], v[94:97], v[208:211], v[70:73]
	v_mfma_f32_16x16x32_bf16 v[66:69], v[102:105], v[208:211], v[66:69]
	v_mfma_f32_16x16x32_bf16 v[150:153], v[98:101], v[166:169], v[150:153]
	v_mfma_f32_16x16x32_bf16 v[146:149], v[110:113], v[166:169], v[146:149]
	v_mfma_f32_16x16x32_bf16 v[134:137], v[98:101], v[196:199], v[134:137]
	v_mfma_f32_16x16x32_bf16 v[130:133], v[110:113], v[196:199], v[130:133]
	v_mfma_f32_16x16x32_bf16 v[118:121], v[98:101], v[204:207], v[118:121]
	v_mfma_f32_16x16x32_bf16 v[114:117], v[110:113], v[204:207], v[114:117]
	v_mfma_f32_16x16x32_bf16 v[70:73], v[98:101], v[212:215], v[70:73]
	v_mfma_f32_16x16x32_bf16 v[66:69], v[110:113], v[212:215], v[66:69]
	s_setprio 2
	s_barrier
	s_add_i32 s55, s55, s65
	v_lshl_add_u64 v[216:217], s[40:41], 0, v[0:1]
	s_mov_b32 m0, s55
	ds_read_b128 v[162:165], v234 offset:16384
	ds_read_b128 v[166:169], v234 offset:17408
	ds_read_b128 v[192:195], v234 offset:18432
	ds_read_b128 v[196:199], v234 offset:19456
	ds_read_b128 v[200:203], v234 offset:20480
	ds_read_b128 v[204:207], v234 offset:21504
	ds_read_b128 v[208:211], v234 offset:22528
	ds_read_b128 v[212:215], v234 offset:23552
	global_load_lds_dwordx4 v[216:217], off
	s_add_i32 m0, s55, 0x2000
	s_add_u32 s62, s40, 0x40000
	v_lshl_add_u64 v[218:219], s[40:41], 0, v[186:187]
	s_addc_u32 s63, s41, 0
	s_add_i32 s55, s57, s65
	global_load_lds_dwordx4 v[218:219], off
	v_lshl_add_u64 v[236:237], s[62:63], 0, v[0:1]
	s_mov_b32 m0, s55
	v_lshl_add_u64 v[238:239], s[60:61], 0, v[184:185]
	global_load_lds_dwordx4 v[236:237], off
	v_lshl_add_u64 v[236:237], s[62:63], 0, v[186:187]
	s_add_i32 m0, s55, 0x2000
	s_nop 0
	global_load_lds_dwordx4 v[236:237], off
	v_lshl_add_u64 v[236:237], s[60:61], 0, v[182:183]
	s_mov_b32 m0, s66
	s_nop 0
	global_load_lds_dwordx4 v[236:237], off
	s_mov_b32 m0, s67
	s_nop 0
	global_load_lds_dwordx4 v[238:239], off
	s_waitcnt lgkmcnt(0)
	s_barrier
; #define PG8_STAGE(bufoff, gbase, voff) do { _Pragma("unroll") for (int _i = 0; _i < 2; ++_i) \
;         __builtin_amdgcn_global_load_lds((const unsigned*)((const char*)(gbase) + (voff)[_i]), (PG8_LAS unsigned*)(lds + (bufoff) + ldsw + _i * 8192), 16, 0, 0); } while (0)
; #define PG8_LDA(dst, b, h) do { _Pragma("unroll") for (int m = 0; m < 4; ++m) _Pragma("unroll") for (int k = 0; k < 2; ++k) dst[m][k] = *(const PG8_LAS bf16x8*)(lds + PG8_SA(b, h) + aoff + m * 2048 + k * 1024); } while (0)
; #define PG8_LDB(dst, b, h) do { _Pragma("unroll") for (int n = 0; n < 2; ++n) _Pragma("unroll") for (int k = 0; k < 2; ++k) dst[n][k] = *(const PG8_LAS bf16x8*)(lds + PG8_SB(b, h) + boff + n * 2048 + k * 1024); } while (0)
; #define PG8_MMA(ai, bj, At, Bt) do { __builtin_amdgcn_s_setprio(1); _Pragma("unroll") for (int m = 0; m < 4; ++m) _Pragma("unroll") for (int n = 0; n < 2; ++n) _Pragma("unroll") for (int k = 0; k < 2; ++k) \
;         acc[ai][bj][m][n] = __builtin_amdgcn_mfma_f32_16x16x32_bf16(Bt[n][k], At[m][k], acc[ai][bj][m][n], 0, 0, 0); __builtin_amdgcn_s_setprio(0); } while (0)
; #define PG8_WAIT_V(n) asm volatile("s_waitcnt vmcnt(" #n ")" ::: "memory")
; template <class Epi, class Sched, bool ALIGN_EPI = false, bool SP2 = false>
; __device__ __forceinline__ void gemm_phase(PG8_LAS unsigned char* lds, const Gemm g, const Sched& S, const Epi& E) {
;     ...
;             PG8_LDB(B0, 0, 0); PG8_LDB(B1, 0, 1); PG8_SCHED; PG8_LDA(At, 0, 0); PG8_STAGE(PG8_SA(1, 1), a1 + hstep, voffA);
;             PG8_WAIT_V(8); PG8_WAIT_L(0); PG8_BAR; PG8_MMA(0, 0, At, B0); PG8_MMA(0, 1, At, B1); PG8_BAR; PG8_SCHED;
;             PG8_LDA(At, 0, 1); PG8_STAGE(PG8_SB(0, 0), b2, voffB); PG8_STAGE(PG8_SB(0, 1), b2 + hstep, voffB); PG8_STAGE(PG8_SA(0, 0), a2, voffA);
;             PG8_WAIT_V(8); PG8_WAIT_L(0); PG8_BAR; PG8_MMA(1, 0, At, B0); PG8_MMA(1, 1, At, B1); PG8_BAR; PG8_SCHED;
;             PG8_LDB(B0, 1, 0); PG8_LDB(B1, 1, 1); PG8_SCHED; PG8_LDA(At, 1, 0); PG8_STAGE(PG8_SA(0, 1), a2 + hstep, voffA);
;             PG8_WAIT_V(8); PG8_WAIT_L(0); PG8_BAR; PG8_MMA(0, 0, At, B0); PG8_MMA(0, 1, At, B1); PG8_BAR; PG8_SCHED;
;             PG8_LDA(At, 1, 1); PG8_STAGE(PG8_SB(1, 0), b3, voffB); PG8_STAGE(PG8_SB(1, 1), b3 + hstep, voffB); PG8_STAGE(PG8_SA(1, 0), a3, voffA);
;             PG8_WAIT_V(8); PG8_WAIT_L(0); PG8_BAR; PG8_MMA(1, 0, At, B0); PG8_MMA(1, 1, At, B1); PG8_BAR; PG8_SCHED;
	s_setprio 1
	s_waitcnt lgkmcnt(0)
	v_mfma_f32_16x16x32_bf16 v[62:65], v[74:77], v[162:165], v[62:65]
	v_mfma_f32_16x16x32_bf16 v[58:61], v[82:85], v[162:165], v[58:61]
	v_mfma_f32_16x16x32_bf16 v[46:49], v[74:77], v[192:195], v[46:49]
	v_mfma_f32_16x16x32_bf16 v[42:45], v[82:85], v[192:195], v[42:45]
	v_mfma_f32_16x16x32_bf16 v[30:33], v[74:77], v[200:203], v[30:33]
	v_mfma_f32_16x16x32_bf16 v[26:29], v[82:85], v[200:203], v[26:29]
	v_mfma_f32_16x16x32_bf16 v[14:17], v[74:77], v[208:211], v[14:17]
	v_mfma_f32_16x16x32_bf16 v[10:13], v[82:85], v[208:211], v[10:13]
	v_mfma_f32_16x16x32_bf16 v[62:65], v[78:81], v[166:169], v[62:65]
	v_mfma_f32_16x16x32_bf16 v[58:61], v[90:93], v[166:169], v[58:61]
	v_mfma_f32_16x16x32_bf16 v[46:49], v[78:81], v[196:199], v[46:49]
	v_mfma_f32_16x16x32_bf16 v[42:45], v[90:93], v[196:199], v[42:45]
	v_mfma_f32_16x16x32_bf16 v[30:33], v[78:81], v[204:207], v[30:33]
	v_mfma_f32_16x16x32_bf16 v[26:29], v[90:93], v[204:207], v[26:29]
	v_mfma_f32_16x16x32_bf16 v[14:17], v[78:81], v[212:215], v[14:17]
	v_mfma_f32_16x16x32_bf16 v[10:13], v[90:93], v[212:215], v[10:13]
	s_setprio 2
	s_setprio 1
	v_mfma_f32_16x16x32_bf16 v[54:57], v[94:97], v[162:165], v[54:57]
	v_mfma_f32_16x16x32_bf16 v[50:53], v[102:105], v[162:165], v[50:53]
	v_mfma_f32_16x16x32_bf16 v[38:41], v[94:97], v[192:195], v[38:41]
	v_mfma_f32_16x16x32_bf16 v[34:37], v[102:105], v[192:195], v[34:37]
	v_mfma_f32_16x16x32_bf16 v[22:25], v[94:97], v[200:203], v[22:25]
	v_mfma_f32_16x16x32_bf16 v[18:21], v[102:105], v[200:203], v[18:21]
	v_mfma_f32_16x16x32_bf16 v[6:9], v[94:97], v[208:211], v[6:9]
	v_mfma_f32_16x16x32_bf16 v[2:5], v[102:105], v[208:211], v[2:5]
	v_mfma_f32_16x16x32_bf16 v[54:57], v[98:101], v[166:169], v[54:57]
	v_mfma_f32_16x16x32_bf16 v[50:53], v[110:113], v[166:169], v[50:53]
	v_mfma_f32_16x16x32_bf16 v[38:41], v[98:101], v[196:199], v[38:41]
	v_mfma_f32_16x16x32_bf16 v[34:37], v[110:113], v[196:199], v[34:37]
	v_mfma_f32_16x16x32_bf16 v[22:25], v[98:101], v[204:207], v[22:25]
	v_mfma_f32_16x16x32_bf16 v[18:21], v[110:113], v[204:207], v[18:21]
	v_mfma_f32_16x16x32_bf16 v[6:9], v[98:101], v[212:215], v[6:9]
	v_mfma_f32_16x16x32_bf16 v[2:5], v[110:113], v[212:215], v[2:5]
	s_setprio 2
	s_barrier
	s_add_i32 s55, 0, 0x18000
	s_add_i32 s57, 0, 0x1c000
	v_add_u32_e32 v90, s55, v233
	v_add_u32_e32 v110, s57, v233
	ds_read_b128 v[74:77], v90
	ds_read_b128 v[78:81], v90 offset:1024
	ds_read_b128 v[82:85], v90 offset:2048
	ds_read_b128 v[90:93], v90 offset:3072
	ds_read_b128 v[94:97], v110
	ds_read_b128 v[98:101], v110 offset:1024
	ds_read_b128 v[102:105], v110 offset:2048
	ds_read_b128 v[110:113], v110 offset:3072
	s_add_u32 s60, s60, 0x40000
	s_addc_u32 s61, s61, 0
	s_mov_b32 m0, s70
	v_lshl_add_u64 v[240:241], s[60:61], 0, v[182:183]
	ds_read_b128 v[162:165], v234 offset:32768
	ds_read_b128 v[166:169], v234 offset:33792
	ds_read_b128 v[192:195], v234 offset:34816
	ds_read_b128 v[196:199], v234 offset:35840
	ds_read_b128 v[200:203], v234 offset:36864
	ds_read_b128 v[204:207], v234 offset:37888
	ds_read_b128 v[208:211], v234 offset:38912
	ds_read_b128 v[212:215], v234 offset:39936
	global_load_lds_dwordx4 v[240:241], off
	v_lshl_add_u64 v[240:241], s[60:61], 0, v[184:185]
	s_mov_b32 m0, s71
	s_nop 0
	global_load_lds_dwordx4 v[240:241], off
	s_waitcnt lgkmcnt(0)
	s_barrier
	s_setprio 1
	s_waitcnt lgkmcnt(0)
	v_mfma_f32_16x16x32_bf16 v[158:161], v[74:77], v[162:165], v[158:161]
	v_mfma_f32_16x16x32_bf16 v[154:157], v[82:85], v[162:165], v[154:157]
	v_mfma_f32_16x16x32_bf16 v[142:145], v[74:77], v[192:195], v[142:145]
	v_mfma_f32_16x16x32_bf16 v[138:141], v[82:85], v[192:195], v[138:141]
	v_mfma_f32_16x16x32_bf16 v[126:129], v[74:77], v[200:203], v[126:129]
	v_mfma_f32_16x16x32_bf16 v[122:125], v[82:85], v[200:203], v[122:125]
	v_mfma_f32_16x16x32_bf16 v[106:109], v[74:77], v[208:211], v[106:109]
	v_mfma_f32_16x16x32_bf16 v[86:89], v[82:85], v[208:211], v[86:89]
	v_mfma_f32_16x16x32_bf16 v[158:161], v[78:81], v[166:169], v[158:161]
	v_mfma_f32_16x16x32_bf16 v[154:157], v[90:93], v[166:169], v[154:157]
	v_mfma_f32_16x16x32_bf16 v[142:145], v[78:81], v[196:199], v[142:145]
	v_mfma_f32_16x16x32_bf16 v[138:141], v[90:93], v[196:199], v[138:141]
	v_mfma_f32_16x16x32_bf16 v[126:129], v[78:81], v[204:207], v[126:129]
	v_mfma_f32_16x16x32_bf16 v[122:125], v[90:93], v[204:207], v[122:125]
	v_mfma_f32_16x16x32_bf16 v[106:109], v[78:81], v[212:215], v[106:109]
	v_mfma_f32_16x16x32_bf16 v[86:89], v[90:93], v[212:215], v[86:89]
	s_setprio 2
	s_setprio 1
	v_mfma_f32_16x16x32_bf16 v[150:153], v[94:97], v[162:165], v[150:153]
	v_mfma_f32_16x16x32_bf16 v[146:149], v[102:105], v[162:165], v[146:149]
	v_mfma_f32_16x16x32_bf16 v[134:137], v[94:97], v[192:195], v[134:137]
	v_mfma_f32_16x16x32_bf16 v[130:133], v[102:105], v[192:195], v[130:133]
	v_mfma_f32_16x16x32_bf16 v[118:121], v[94:97], v[200:203], v[118:121]
	v_mfma_f32_16x16x32_bf16 v[114:117], v[102:105], v[200:203], v[114:117]
	v_mfma_f32_16x16x32_bf16 v[70:73], v[94:97], v[208:211], v[70:73]
	v_mfma_f32_16x16x32_bf16 v[66:69], v[102:105], v[208:211], v[66:69]
	v_mfma_f32_16x16x32_bf16 v[150:153], v[98:101], v[166:169], v[150:153]
	v_mfma_f32_16x16x32_bf16 v[146:149], v[110:113], v[166:169], v[146:149]
	v_mfma_f32_16x16x32_bf16 v[134:137], v[98:101], v[196:199], v[134:137]
	v_mfma_f32_16x16x32_bf16 v[130:133], v[110:113], v[196:199], v[130:133]
	v_mfma_f32_16x16x32_bf16 v[118:121], v[98:101], v[204:207], v[118:121]
	v_mfma_f32_16x16x32_bf16 v[114:117], v[110:113], v[204:207], v[114:117]
	v_mfma_f32_16x16x32_bf16 v[70:73], v[98:101], v[212:215], v[70:73]
	v_mfma_f32_16x16x32_bf16 v[66:69], v[110:113], v[212:215], v[66:69]
	s_setprio 2
	s_barrier
; #define PG8_STAGE(bufoff, gbase, voff) do { _Pragma("unroll") for (int _i = 0; _i < 2; ++_i) \
;         __builtin_amdgcn_global_load_lds((const unsigned*)((const char*)(gbase) + (voff)[_i]), (PG8_LAS unsigned*)(lds + (bufoff) + ldsw + _i * 8192), 16, 0, 0); } while (0)
; #define PG8_LDA(dst, b, h) do { _Pragma("unroll") for (int m = 0; m < 4; ++m) _Pragma("unroll") for (int k = 0; k < 2; ++k) dst[m][k] = *(const PG8_LAS bf16x8*)(lds + PG8_SA(b, h) + aoff + m * 2048 + k * 1024); } while (0)
; #define PG8_LDB(dst, b, h) do { _Pragma("unroll") for (int n = 0; n < 2; ++n) _Pragma("unroll") for (int k = 0; k < 2; ++k) dst[n][k] = *(const PG8_LAS bf16x8*)(lds + PG8_SB(b, h) + boff + n * 2048 + k * 1024); } while (0)
; template <class Epi, class Sched, bool ALIGN_EPI = false, bool SP2 = false>
; __device__ __forceinline__ void gemm_phase(PG8_LAS unsigned char* lds, const Gemm g, const Sched& S, const Epi& E) {
;     ...
;         for (int t = 0; t < nt; t += 2) {
;             const bool last = (t == nt - 2);
;             const char* a1 = cA + (size_t)(t + 1) * kstep;
;             const char* a2 = last ? nA : cA + (size_t)(t + 2) * kstep; const char* b2 = last ? nB : cB + (size_t)(t + 2) * kstep;
;             const char* a3 = a2 + kstep; const char* b3 = b2 + kstep;
;             if (last && has_next) S.a_ready(nxt);
;             if constexpr (SP2) {
;             PG8_LDB(B0, 0, 0); PG8_LDB(B1, 0, 1); PG8_SCHED; PG8_LDA(At, 0, 0); PG8_STAGE(PG8_SA(1, 1), a1 + hstep, voffA);
;             PG8_WAIT_V(8); PG8_WAIT_L(0); PG8_BAR; PG8_MMA(0, 0, At, B0); PG8_MMA(0, 1, At, B1); PG8_BAR; PG8_SCHED;
;             PG8_LDA(At, 0, 1); PG8_STAGE(PG8_SB(0, 0), b2, voffB); PG8_STAGE(PG8_SB(0, 1), b2 + hstep, voffB); PG8_STAGE(PG8_SA(0, 0), a2, voffA);
;             PG8_WAIT_V(8); PG8_WAIT_L(0); PG8_BAR; PG8_MMA(1, 0, At, B0); PG8_MMA(1, 1, At, B1); PG8_BAR; PG8_SCHED;
;             PG8_LDB(B0, 1, 0); PG8_LDB(B1, 1, 1); PG8_SCHED; PG8_LDA(At, 1, 0); PG8_STAGE(PG8_SA(0, 1), a2 + hstep, voffA);
;             PG8_WAIT_V(8); PG8_WAIT_L(0); PG8_BAR; PG8_MMA(0, 0, At, B0); PG8_MMA(0, 1, At, B1); PG8_BAR; PG8_SCHED;
;             PG8_LDA(At, 1, 1); PG8_STAGE(PG8_SB(1, 0), b3, voffB); PG8_STAGE(PG8_SB(1, 1), b3 + hstep, voffB); PG8_STAGE(PG8_SA(1, 0), a3, voffA);
;             PG8_WAIT_V(8); PG8_WAIT_L(0); PG8_BAR; PG8_MMA(1, 0, At, B0); PG8_MMA(1, 1, At, B1); PG8_BAR; PG8_SCHED;
	s_add_i32 s55, s55, s65
	v_lshl_add_u64 v[216:217], v[216:217], 0, s[36:37]
	s_mov_b32 m0, s55
	ds_read_b128 v[162:165], v234 offset:49152
	ds_read_b128 v[166:169], v234 offset:50176
	ds_read_b128 v[192:195], v234 offset:51200
	ds_read_b128 v[196:199], v234 offset:52224
	ds_read_b128 v[200:203], v234 offset:53248
	ds_read_b128 v[204:207], v234 offset:54272
	ds_read_b128 v[208:211], v234 offset:55296
	ds_read_b128 v[212:215], v234 offset:56320
	global_load_lds_dwordx4 v[216:217], off
	s_add_i32 m0, s55, 0x2000
	s_add_u32 s40, s40, 0x40080
	v_lshl_add_u64 v[216:217], v[218:219], 0, s[36:37]
	s_addc_u32 s41, s41, 0
	s_add_i32 s55, s57, s65
	global_load_lds_dwordx4 v[216:217], off
	v_lshl_add_u64 v[216:217], s[40:41], 0, v[0:1]
	s_mov_b32 m0, s55
	s_nop 0
	global_load_lds_dwordx4 v[216:217], off
	v_lshl_add_u64 v[216:217], s[40:41], 0, v[186:187]
	s_add_i32 m0, s55, 0x2000
	s_nop 0
	global_load_lds_dwordx4 v[216:217], off
	v_lshl_add_u64 v[216:217], v[236:237], 0, s[36:37]
	s_mov_b32 m0, s76
	s_nop 0
	global_load_lds_dwordx4 v[216:217], off
	v_lshl_add_u64 v[216:217], v[238:239], 0, s[36:37]
	s_mov_b32 m0, s77
	s_nop 0
	global_load_lds_dwordx4 v[216:217], off
	s_waitcnt vmcnt(8)
	s_waitcnt lgkmcnt(0)
	s_barrier
	s_setprio 1
	s_waitcnt lgkmcnt(0)
	v_mfma_f32_16x16x32_bf16 v[62:65], v[74:77], v[162:165], v[62:65]
	v_mfma_f32_16x16x32_bf16 v[58:61], v[82:85], v[162:165], v[58:61]
	v_mfma_f32_16x16x32_bf16 v[46:49], v[74:77], v[192:195], v[46:49]
	v_mfma_f32_16x16x32_bf16 v[42:45], v[82:85], v[192:195], v[42:45]
	v_mfma_f32_16x16x32_bf16 v[30:33], v[74:77], v[200:203], v[30:33]
	v_mfma_f32_16x16x32_bf16 v[26:29], v[82:85], v[200:203], v[26:29]
	v_mfma_f32_16x16x32_bf16 v[14:17], v[74:77], v[208:211], v[14:17]
	v_mfma_f32_16x16x32_bf16 v[10:13], v[82:85], v[208:211], v[10:13]
	v_mfma_f32_16x16x32_bf16 v[62:65], v[78:81], v[166:169], v[62:65]
	v_mfma_f32_16x16x32_bf16 v[58:61], v[90:93], v[166:169], v[58:61]
	v_mfma_f32_16x16x32_bf16 v[46:49], v[78:81], v[196:199], v[46:49]
	v_mfma_f32_16x16x32_bf16 v[42:45], v[90:93], v[196:199], v[42:45]
	v_mfma_f32_16x16x32_bf16 v[30:33], v[78:81], v[204:207], v[30:33]
	v_mfma_f32_16x16x32_bf16 v[26:29], v[90:93], v[204:207], v[26:29]
	v_mfma_f32_16x16x32_bf16 v[14:17], v[78:81], v[212:215], v[14:17]
	v_mfma_f32_16x16x32_bf16 v[10:13], v[90:93], v[212:215], v[10:13]
	s_setprio 2
	s_setprio 1
	v_mfma_f32_16x16x32_bf16 v[54:57], v[94:97], v[162:165], v[54:57]
	v_mfma_f32_16x16x32_bf16 v[50:53], v[102:105], v[162:165], v[50:53]
	v_mfma_f32_16x16x32_bf16 v[38:41], v[94:97], v[192:195], v[38:41]
	v_mfma_f32_16x16x32_bf16 v[34:37], v[102:105], v[192:195], v[34:37]
	v_mfma_f32_16x16x32_bf16 v[22:25], v[94:97], v[200:203], v[22:25]
	v_mfma_f32_16x16x32_bf16 v[18:21], v[102:105], v[200:203], v[18:21]
	v_mfma_f32_16x16x32_bf16 v[6:9], v[94:97], v[208:211], v[6:9]
	v_mfma_f32_16x16x32_bf16 v[2:5], v[102:105], v[208:211], v[2:5]
	v_mfma_f32_16x16x32_bf16 v[54:57], v[98:101], v[166:169], v[54:57]
	v_mfma_f32_16x16x32_bf16 v[50:53], v[110:113], v[166:169], v[50:53]
	v_mfma_f32_16x16x32_bf16 v[38:41], v[98:101], v[196:199], v[38:41]
	v_mfma_f32_16x16x32_bf16 v[34:37], v[110:113], v[196:199], v[34:37]
	v_mfma_f32_16x16x32_bf16 v[22:25], v[98:101], v[204:207], v[22:25]
	v_mfma_f32_16x16x32_bf16 v[18:21], v[110:113], v[204:207], v[18:21]
	v_mfma_f32_16x16x32_bf16 v[6:9], v[98:101], v[212:215], v[6:9]
	v_mfma_f32_16x16x32_bf16 v[2:5], v[110:113], v[212:215], v[2:5]
	s_setprio 2
	s_barrier
	s_add_i32 s49, s49, 2
	s_add_u32 s22, s22, 0x100
	s_addc_u32 s23, s23, 0
	s_add_u32 s45, s45, 0x100
	s_addc_u32 s47, s47, 0
	s_cmp_gt_u32 s49, 13
	s_cbranch_scc0 .LBB0_157
	s_branch .Lafter_157
.LBB0_157:
	s_add_u32 s40, s22, 0xfffc0080
	s_addc_u32 s41, s23, -1
	s_add_i32 s55, 0, 0x10000
	s_cmp_eq_u32 s49, 12
	s_cselect_b32 s61, s5, s41
	s_cselect_b32 s60, s7, s40
	s_cselect_b32 s41, s34, s47
	s_cselect_b32 s40, s35, s45
	s_add_i32 s57, 0, 0x14000
	v_add_u32_e32 v90, s55, v233
	v_add_u32_e32 v110, s57, v233
	ds_read_b128 v[74:77], v90
	ds_read_b128 v[78:81], v90 offset:1024
	ds_read_b128 v[82:85], v90 offset:2048
	ds_read_b128 v[90:93], v90 offset:3072
	ds_read_b128 v[94:97], v110
	ds_read_b128 v[98:101], v110 offset:1024
	ds_read_b128 v[102:105], v110 offset:2048
	ds_read_b128 v[110:113], v110 offset:3072
	v_lshl_add_u64 v[216:217], s[22:23], 0, v[188:189]
	s_add_i32 m0, s66, 0xc000
	ds_read_b128 v[162:165], v234
	ds_read_b128 v[166:169], v234 offset:1024
	ds_read_b128 v[192:195], v234 offset:2048
	ds_read_b128 v[196:199], v234 offset:3072
	ds_read_b128 v[200:203], v234 offset:4096
	ds_read_b128 v[204:207], v234 offset:5120
	ds_read_b128 v[208:211], v234 offset:6144
	ds_read_b128 v[212:215], v234 offset:7168
	global_load_lds_dwordx4 v[216:217], off
	v_lshl_add_u64 v[216:217], s[22:23], 0, v[190:191]
	s_add_i32 m0, s66, 0xe000
	s_nop 0
	global_load_lds_dwordx4 v[216:217], off
	s_waitcnt vmcnt(8)
	s_waitcnt lgkmcnt(0)
	s_barrier
; #define PG8_STAGE(bufoff, gbase, voff) do { _Pragma("unroll") for (int _i = 0; _i < 2; ++_i) \
;         __builtin_amdgcn_global_load_lds((const unsigned*)((const char*)(gbase) + (voff)[_i]), (PG8_LAS unsigned*)(lds + (bufoff) + ldsw + _i * 8192), 16, 0, 0); } while (0)
; #define PG8_LDA(dst, b, h) do { _Pragma("unroll") for (int m = 0; m < 4; ++m) _Pragma("unroll") for (int k = 0; k < 2; ++k) dst[m][k] = *(const PG8_LAS bf16x8*)(lds + PG8_SA(b, h) + aoff + m * 2048 + k * 1024); } while (0)
; #define PG8_LDB(dst, b, h) do { _Pragma("unroll") for (int n = 0; n < 2; ++n) _Pragma("unroll") for (int k = 0; k < 2; ++k) dst[n][k] = *(const PG8_LAS bf16x8*)(lds + PG8_SB(b, h) + boff + n * 2048 + k * 1024); } while (0)
; #define PG8_MMA(ai, bj, At, Bt) do { __builtin_amdgcn_s_setprio(1); _Pragma("unroll") for (int m = 0; m < 4; ++m) _Pragma("unroll") for (int n = 0; n < 2; ++n) _Pragma("unroll") for (int k = 0; k < 2; ++k) \
;         acc[ai][bj][m][n] = __builtin_amdgcn_mfma_f32_16x16x32_bf16(Bt[n][k], At[m][k], acc[ai][bj][m][n], 0, 0, 0); __builtin_amdgcn_s_setprio(0); } while (0)
; #define PG8_WAIT_V(n) asm volatile("s_waitcnt vmcnt(" #n ")" ::: "memory")
; #define PG8_WAIT_L(n) asm volatile("s_waitcnt lgkmcnt(" #n ")" ::: "memory")
; #define PG8_BAR __builtin_amdgcn_s_barrier()
; #define PG8_SCHED __builtin_amdgcn_sched_barrier(0)
; template <class Epi, class Sched, bool ALIGN_EPI = false, bool SP2 = false>
; __device__ __forceinline__ void gemm_phase(PG8_LAS unsigned char* lds, const Gemm g, const Sched& S, const Epi& E) {
;     ...
;             PG8_LDB(B0, 0, 0); PG8_LDB(B1, 0, 1); PG8_SCHED; PG8_LDA(At, 0, 0); PG8_STAGE(PG8_SA(1, 1), a1 + hstep, voffA);
;             PG8_WAIT_V(8); PG8_WAIT_L(0); PG8_BAR; PG8_MMA(0, 0, At, B0); PG8_MMA(0, 1, At, B1); PG8_BAR; PG8_SCHED;
;             PG8_LDA(At, 0, 1); PG8_STAGE(PG8_SB(0, 0), b2, voffB); PG8_STAGE(PG8_SB(0, 1), b2 + hstep, voffB); PG8_STAGE(PG8_SA(0, 0), a2, voffA);
;             PG8_WAIT_V(8); PG8_WAIT_L(0); PG8_BAR; PG8_MMA(1, 0, At, B0); PG8_MMA(1, 1, At, B1); PG8_BAR; PG8_SCHED;
	s_setprio 1
	s_waitcnt lgkmcnt(0)
	v_mfma_f32_16x16x32_bf16 v[158:161], v[74:77], v[162:165], v[158:161]
	v_mfma_f32_16x16x32_bf16 v[154:157], v[82:85], v[162:165], v[154:157]
	v_mfma_f32_16x16x32_bf16 v[142:145], v[74:77], v[192:195], v[142:145]
	v_mfma_f32_16x16x32_bf16 v[138:141], v[82:85], v[192:195], v[138:141]
	v_mfma_f32_16x16x32_bf16 v[126:129], v[74:77], v[200:203], v[126:129]
	v_mfma_f32_16x16x32_bf16 v[122:125], v[82:85], v[200:203], v[122:125]
	v_mfma_f32_16x16x32_bf16 v[106:109], v[74:77], v[208:211], v[106:109]
	v_mfma_f32_16x16x32_bf16 v[86:89], v[82:85], v[208:211], v[86:89]
	v_mfma_f32_16x16x32_bf16 v[158:161], v[78:81], v[166:169], v[158:161]
	v_mfma_f32_16x16x32_bf16 v[154:157], v[90:93], v[166:169], v[154:157]
	v_mfma_f32_16x16x32_bf16 v[142:145], v[78:81], v[196:199], v[142:145]
	v_mfma_f32_16x16x32_bf16 v[138:141], v[90:93], v[196:199], v[138:141]
	v_mfma_f32_16x16x32_bf16 v[126:129], v[78:81], v[204:207], v[126:129]
	v_mfma_f32_16x16x32_bf16 v[122:125], v[90:93], v[204:207], v[122:125]
	v_mfma_f32_16x16x32_bf16 v[106:109], v[78:81], v[212:215], v[106:109]
	v_mfma_f32_16x16x32_bf16 v[86:89], v[90:93], v[212:215], v[86:89]
	s_setprio 2
	s_setprio 1
	v_mfma_f32_16x16x32_bf16 v[150:153], v[94:97], v[162:165], v[150:153]
	v_mfma_f32_16x16x32_bf16 v[146:149], v[102:105], v[162:165], v[146:149]
	v_mfma_f32_16x16x32_bf16 v[134:137], v[94:97], v[192:195], v[134:137]
	v_mfma_f32_16x16x32_bf16 v[130:133], v[102:105], v[192:195], v[130:133]
	v_mfma_f32_16x16x32_bf16 v[118:121], v[94:97], v[200:203], v[118:121]
	v_mfma_f32_16x16x32_bf16 v[114:117], v[102:105], v[200:203], v[114:117]
	v_mfma_f32_16x16x32_bf16 v[70:73], v[94:97], v[208:211], v[70:73]
	v_mfma_f32_16x16x32_bf16 v[66:69], v[102:105], v[208:211], v[66:69]
	v_mfma_f32_16x16x32_bf16 v[150:153], v[98:101], v[166:169], v[150:153]
	v_mfma_f32_16x16x32_bf16 v[146:149], v[110:113], v[166:169], v[146:149]
	v_mfma_f32_16x16x32_bf16 v[134:137], v[98:101], v[196:199], v[134:137]
	v_mfma_f32_16x16x32_bf16 v[130:133], v[110:113], v[196:199], v[130:133]
	v_mfma_f32_16x16x32_bf16 v[118:121], v[98:101], v[204:207], v[118:121]
	v_mfma_f32_16x16x32_bf16 v[114:117], v[110:113], v[204:207], v[114:117]
	v_mfma_f32_16x16x32_bf16 v[70:73], v[98:101], v[212:215], v[70:73]
	v_mfma_f32_16x16x32_bf16 v[66:69], v[110:113], v[212:215], v[66:69]
	s_setprio 2
	s_barrier
	s_add_i32 s55, s55, s65
	v_lshl_add_u64 v[216:217], s[40:41], 0, v[0:1]
	s_mov_b32 m0, s55
	ds_read_b128 v[162:165], v234 offset:16384
	ds_read_b128 v[166:169], v234 offset:17408
	ds_read_b128 v[192:195], v234 offset:18432
	ds_read_b128 v[196:199], v234 offset:19456
	ds_read_b128 v[200:203], v234 offset:20480
	ds_read_b128 v[204:207], v234 offset:21504
	ds_read_b128 v[208:211], v234 offset:22528
	ds_read_b128 v[212:215], v234 offset:23552
	global_load_lds_dwordx4 v[216:217], off
	s_add_i32 m0, s55, 0x2000
	s_add_u32 s62, s40, 0x40000
	v_lshl_add_u64 v[218:219], s[40:41], 0, v[186:187]
	s_addc_u32 s63, s41, 0
	s_add_i32 s55, s57, s65
	global_load_lds_dwordx4 v[218:219], off
	v_lshl_add_u64 v[236:237], s[62:63], 0, v[0:1]
	s_mov_b32 m0, s55
	v_lshl_add_u64 v[238:239], s[60:61], 0, v[184:185]
	global_load_lds_dwordx4 v[236:237], off
	v_lshl_add_u64 v[236:237], s[62:63], 0, v[186:187]
	s_add_i32 m0, s55, 0x2000
	s_nop 0
	global_load_lds_dwordx4 v[236:237], off
	v_lshl_add_u64 v[236:237], s[60:61], 0, v[182:183]
	s_mov_b32 m0, s66
	s_nop 0
	global_load_lds_dwordx4 v[236:237], off
	s_mov_b32 m0, s67
	s_nop 0
	global_load_lds_dwordx4 v[238:239], off
	s_waitcnt vmcnt(8)
	s_waitcnt lgkmcnt(0)
	s_barrier
	s_setprio 1
	s_waitcnt lgkmcnt(0)
	v_mfma_f32_16x16x32_bf16 v[62:65], v[74:77], v[162:165], v[62:65]
	v_mfma_f32_16x16x32_bf16 v[58:61], v[82:85], v[162:165], v[58:61]
	v_mfma_f32_16x16x32_bf16 v[46:49], v[74:77], v[192:195], v[46:49]
	v_mfma_f32_16x16x32_bf16 v[42:45], v[82:85], v[192:195], v[42:45]
	v_mfma_f32_16x16x32_bf16 v[30:33], v[74:77], v[200:203], v[30:33]
	v_mfma_f32_16x16x32_bf16 v[26:29], v[82:85], v[200:203], v[26:29]
	v_mfma_f32_16x16x32_bf16 v[14:17], v[74:77], v[208:211], v[14:17]
	v_mfma_f32_16x16x32_bf16 v[10:13], v[82:85], v[208:211], v[10:13]
	v_mfma_f32_16x16x32_bf16 v[62:65], v[78:81], v[166:169], v[62:65]
	v_mfma_f32_16x16x32_bf16 v[58:61], v[90:93], v[166:169], v[58:61]
	v_mfma_f32_16x16x32_bf16 v[46:49], v[78:81], v[196:199], v[46:49]
	v_mfma_f32_16x16x32_bf16 v[42:45], v[90:93], v[196:199], v[42:45]
	v_mfma_f32_16x16x32_bf16 v[30:33], v[78:81], v[204:207], v[30:33]
	v_mfma_f32_16x16x32_bf16 v[26:29], v[90:93], v[204:207], v[26:29]
	v_mfma_f32_16x16x32_bf16 v[14:17], v[78:81], v[212:215], v[14:17]
	v_mfma_f32_16x16x32_bf16 v[10:13], v[90:93], v[212:215], v[10:13]
	s_setprio 2
	s_setprio 1
	v_mfma_f32_16x16x32_bf16 v[54:57], v[94:97], v[162:165], v[54:57]
	v_mfma_f32_16x16x32_bf16 v[50:53], v[102:105], v[162:165], v[50:53]
	v_mfma_f32_16x16x32_bf16 v[38:41], v[94:97], v[192:195], v[38:41]
	v_mfma_f32_16x16x32_bf16 v[34:37], v[102:105], v[192:195], v[34:37]
	v_mfma_f32_16x16x32_bf16 v[22:25], v[94:97], v[200:203], v[22:25]
	v_mfma_f32_16x16x32_bf16 v[18:21], v[102:105], v[200:203], v[18:21]
	v_mfma_f32_16x16x32_bf16 v[6:9], v[94:97], v[208:211], v[6:9]
	v_mfma_f32_16x16x32_bf16 v[2:5], v[102:105], v[208:211], v[2:5]
	v_mfma_f32_16x16x32_bf16 v[54:57], v[98:101], v[166:169], v[54:57]
	v_mfma_f32_16x16x32_bf16 v[50:53], v[110:113], v[166:169], v[50:53]
	v_mfma_f32_16x16x32_bf16 v[38:41], v[98:101], v[196:199], v[38:41]
	v_mfma_f32_16x16x32_bf16 v[34:37], v[110:113], v[196:199], v[34:37]
	v_mfma_f32_16x16x32_bf16 v[22:25], v[98:101], v[204:207], v[22:25]
	v_mfma_f32_16x16x32_bf16 v[18:21], v[110:113], v[204:207], v[18:21]
	v_mfma_f32_16x16x32_bf16 v[6:9], v[98:101], v[212:215], v[6:9]
	v_mfma_f32_16x16x32_bf16 v[2:5], v[110:113], v[212:215], v[2:5]
	s_setprio 2
	s_barrier
; #define PG8_STAGE(bufoff, gbase, voff) do { _Pragma("unroll") for (int _i = 0; _i < 2; ++_i) \
;         __builtin_amdgcn_global_load_lds((const unsigned*)((const char*)(gbase) + (voff)[_i]), (PG8_LAS unsigned*)(lds + (bufoff) + ldsw + _i * 8192), 16, 0, 0); } while (0)
; #define PG8_LDA(dst, b, h) do { _Pragma("unroll") for (int m = 0; m < 4; ++m) _Pragma("unroll") for (int k = 0; k < 2; ++k) dst[m][k] = *(const PG8_LAS bf16x8*)(lds + PG8_SA(b, h) + aoff + m * 2048 + k * 1024); } while (0)
; #define PG8_LDB(dst, b, h) do { _Pragma("unroll") for (int n = 0; n < 2; ++n) _Pragma("unroll") for (int k = 0; k < 2; ++k) dst[n][k] = *(const PG8_LAS bf16x8*)(lds + PG8_SB(b, h) + boff + n * 2048 + k * 1024); } while (0)
; #define PG8_MMA(ai, bj, At, Bt) do { __builtin_amdgcn_s_setprio(1); _Pragma("unroll") for (int m = 0; m < 4; ++m) _Pragma("unroll") for (int n = 0; n < 2; ++n) _Pragma("unroll") for (int k = 0; k < 2; ++k) \
;         acc[ai][bj][m][n] = __builtin_amdgcn_mfma_f32_16x16x32_bf16(Bt[n][k], At[m][k], acc[ai][bj][m][n], 0, 0, 0); __builtin_amdgcn_s_setprio(0); } while (0)
; #define PG8_WAIT_V(n) asm volatile("s_waitcnt vmcnt(" #n ")" ::: "memory")
; #define PG8_WAIT_L(n) asm volatile("s_waitcnt lgkmcnt(" #n ")" ::: "memory")
; #define PG8_BAR __builtin_amdgcn_s_barrier()
; #define PG8_SCHED __builtin_amdgcn_sched_barrier(0)
; template <class Epi, class Sched, bool ALIGN_EPI = false, bool SP2 = false>
; __device__ __forceinline__ void gemm_phase(PG8_LAS unsigned char* lds, const Gemm g, const Sched& S, const Epi& E) {
;     ...
;             PG8_LDB(B0, 1, 0); PG8_LDB(B1, 1, 1); PG8_SCHED; PG8_LDA(At, 1, 0); PG8_STAGE(PG8_SA(0, 1), a2 + hstep, voffA);
;             PG8_WAIT_V(8); PG8_WAIT_L(0); PG8_BAR; PG8_MMA(0, 0, At, B0); PG8_MMA(0, 1, At, B1); PG8_BAR; PG8_SCHED;
	s_add_i32 s55, 0, 0x18000
	s_add_i32 s57, 0, 0x1c000
	v_add_u32_e32 v90, s55, v233
	v_add_u32_e32 v110, s57, v233
	ds_read_b128 v[74:77], v90
	ds_read_b128 v[78:81], v90 offset:1024
	ds_read_b128 v[82:85], v90 offset:2048
	ds_read_b128 v[90:93], v90 offset:3072
	ds_read_b128 v[94:97], v110
	ds_read_b128 v[98:101], v110 offset:1024
	ds_read_b128 v[102:105], v110 offset:2048
	ds_read_b128 v[110:113], v110 offset:3072
	s_add_u32 s60, s60, 0x40000
	s_addc_u32 s61, s61, 0
	s_mov_b32 m0, s70
	v_lshl_add_u64 v[240:241], s[60:61], 0, v[182:183]
	ds_read_b128 v[162:165], v234 offset:32768
	ds_read_b128 v[166:169], v234 offset:33792
	ds_read_b128 v[192:195], v234 offset:34816
	ds_read_b128 v[196:199], v234 offset:35840
	ds_read_b128 v[200:203], v234 offset:36864
	ds_read_b128 v[204:207], v234 offset:37888
	ds_read_b128 v[208:211], v234 offset:38912
	ds_read_b128 v[212:215], v234 offset:39936
	global_load_lds_dwordx4 v[240:241], off
	v_lshl_add_u64 v[240:241], s[60:61], 0, v[184:185]
	s_mov_b32 m0, s71
	s_nop 0
	global_load_lds_dwordx4 v[240:241], off
	s_waitcnt vmcnt(8)
	s_waitcnt lgkmcnt(0)
	s_barrier
	s_setprio 1
	s_waitcnt lgkmcnt(0)
	v_mfma_f32_16x16x32_bf16 v[158:161], v[74:77], v[162:165], v[158:161]
	v_mfma_f32_16x16x32_bf16 v[154:157], v[82:85], v[162:165], v[154:157]
	v_mfma_f32_16x16x32_bf16 v[142:145], v[74:77], v[192:195], v[142:145]
	v_mfma_f32_16x16x32_bf16 v[138:141], v[82:85], v[192:195], v[138:141]
	v_mfma_f32_16x16x32_bf16 v[126:129], v[74:77], v[200:203], v[126:129]
	v_mfma_f32_16x16x32_bf16 v[122:125], v[82:85], v[200:203], v[122:125]
	v_mfma_f32_16x16x32_bf16 v[106:109], v[74:77], v[208:211], v[106:109]
	v_mfma_f32_16x16x32_bf16 v[86:89], v[82:85], v[208:211], v[86:89]
	v_mfma_f32_16x16x32_bf16 v[158:161], v[78:81], v[166:169], v[158:161]
	v_mfma_f32_16x16x32_bf16 v[154:157], v[90:93], v[166:169], v[154:157]
	v_mfma_f32_16x16x32_bf16 v[142:145], v[78:81], v[196:199], v[142:145]
	v_mfma_f32_16x16x32_bf16 v[138:141], v[90:93], v[196:199], v[138:141]
	v_mfma_f32_16x16x32_bf16 v[126:129], v[78:81], v[204:207], v[126:129]
	v_mfma_f32_16x16x32_bf16 v[122:125], v[90:93], v[204:207], v[122:125]
	v_mfma_f32_16x16x32_bf16 v[106:109], v[78:81], v[212:215], v[106:109]
	v_mfma_f32_16x16x32_bf16 v[86:89], v[90:93], v[212:215], v[86:89]
	s_setprio 2
	s_setprio 1
	v_mfma_f32_16x16x32_bf16 v[150:153], v[94:97], v[162:165], v[150:153]
	v_mfma_f32_16x16x32_bf16 v[146:149], v[102:105], v[162:165], v[146:149]
	v_mfma_f32_16x16x32_bf16 v[134:137], v[94:97], v[192:195], v[134:137]
	v_mfma_f32_16x16x32_bf16 v[130:133], v[102:105], v[192:195], v[130:133]
	v_mfma_f32_16x16x32_bf16 v[118:121], v[94:97], v[200:203], v[118:121]
	v_mfma_f32_16x16x32_bf16 v[114:117], v[102:105], v[200:203], v[114:117]
	v_mfma_f32_16x16x32_bf16 v[70:73], v[94:97], v[208:211], v[70:73]
	v_mfma_f32_16x16x32_bf16 v[66:69], v[102:105], v[208:211], v[66:69]
	v_mfma_f32_16x16x32_bf16 v[150:153], v[98:101], v[166:169], v[150:153]
	v_mfma_f32_16x16x32_bf16 v[146:149], v[110:113], v[166:169], v[146:149]
	v_mfma_f32_16x16x32_bf16 v[134:137], v[98:101], v[196:199], v[134:137]
	v_mfma_f32_16x16x32_bf16 v[130:133], v[110:113], v[196:199], v[130:133]
	v_mfma_f32_16x16x32_bf16 v[118:121], v[98:101], v[204:207], v[118:121]
	v_mfma_f32_16x16x32_bf16 v[114:117], v[110:113], v[204:207], v[114:117]
	v_mfma_f32_16x16x32_bf16 v[70:73], v[98:101], v[212:215], v[70:73]
	v_mfma_f32_16x16x32_bf16 v[66:69], v[110:113], v[212:215], v[66:69]
	s_setprio 2
	s_barrier
; #define PG8_STAGE(bufoff, gbase, voff) do { _Pragma("unroll") for (int _i = 0; _i < 2; ++_i) \
;         __builtin_amdgcn_global_load_lds((const unsigned*)((const char*)(gbase) + (voff)[_i]), (PG8_LAS unsigned*)(lds + (bufoff) + ldsw + _i * 8192), 16, 0, 0); } while (0)
; #define PG8_LDA(dst, b, h) do { _Pragma("unroll") for (int m = 0; m < 4; ++m) _Pragma("unroll") for (int k = 0; k < 2; ++k) dst[m][k] = *(const PG8_LAS bf16x8*)(lds + PG8_SA(b, h) + aoff + m * 2048 + k * 1024); } while (0)
; #define PG8_LDB(dst, b, h) do { _Pragma("unroll") for (int n = 0; n < 2; ++n) _Pragma("unroll") for (int k = 0; k < 2; ++k) dst[n][k] = *(const PG8_LAS bf16x8*)(lds + PG8_SB(b, h) + boff + n * 2048 + k * 1024); } while (0)
; template <class Epi, class Sched, bool ALIGN_EPI = false, bool SP2 = false>
; __device__ __forceinline__ void gemm_phase(PG8_LAS unsigned char* lds, const Gemm g, const Sched& S, const Epi& E) {
;     ...
;         for (int t = 0; t < nt; t += 2) {
;             const bool last = (t == nt - 2);
;             const char* a1 = cA + (size_t)(t + 1) * kstep;
;             const char* a2 = last ? nA : cA + (size_t)(t + 2) * kstep; const char* b2 = last ? nB : cB + (size_t)(t + 2) * kstep;
;             const char* a3 = a2 + kstep; const char* b3 = b2 + kstep;
;             if (last && has_next) S.a_ready(nxt);
;             if constexpr (SP2) {
;             PG8_LDB(B0, 0, 0); PG8_LDB(B1, 0, 1); PG8_SCHED; PG8_LDA(At, 0, 0); PG8_STAGE(PG8_SA(1, 1), a1 + hstep, voffA);
;             PG8_WAIT_V(8); PG8_WAIT_L(0); PG8_BAR; PG8_MMA(0, 0, At, B0); PG8_MMA(0, 1, At, B1); PG8_BAR; PG8_SCHED;
;             PG8_LDA(At, 0, 1); PG8_STAGE(PG8_SB(0, 0), b2, voffB); PG8_STAGE(PG8_SB(0, 1), b2 + hstep, voffB); PG8_STAGE(PG8_SA(0, 0), a2, voffA);
;             PG8_WAIT_V(8); PG8_WAIT_L(0); PG8_BAR; PG8_MMA(1, 0, At, B0); PG8_MMA(1, 1, At, B1); PG8_BAR; PG8_SCHED;
;             PG8_LDB(B0, 1, 0); PG8_LDB(B1, 1, 1); PG8_SCHED; PG8_LDA(At, 1, 0); PG8_STAGE(PG8_SA(0, 1), a2 + hstep, voffA);
;             PG8_WAIT_V(8); PG8_WAIT_L(0); PG8_BAR; PG8_MMA(0, 0, At, B0); PG8_MMA(0, 1, At, B1); PG8_BAR; PG8_SCHED;
;             PG8_LDA(At, 1, 1); PG8_STAGE(PG8_SB(1, 0), b3, voffB); PG8_STAGE(PG8_SB(1, 1), b3 + hstep, voffB); PG8_STAGE(PG8_SA(1, 0), a3, voffA);
;             PG8_WAIT_V(8); PG8_WAIT_L(0); PG8_BAR; PG8_MMA(1, 0, At, B0); PG8_MMA(1, 1, At, B1); PG8_BAR; PG8_SCHED;
	s_add_i32 s55, s55, s65
	v_lshl_add_u64 v[216:217], v[216:217], 0, s[36:37]
	s_mov_b32 m0, s55
	ds_read_b128 v[162:165], v234 offset:49152
	ds_read_b128 v[166:169], v234 offset:50176
	ds_read_b128 v[192:195], v234 offset:51200
	ds_read_b128 v[196:199], v234 offset:52224
	ds_read_b128 v[200:203], v234 offset:53248
	ds_read_b128 v[204:207], v234 offset:54272
	ds_read_b128 v[208:211], v234 offset:55296
	ds_read_b128 v[212:215], v234 offset:56320
	global_load_lds_dwordx4 v[216:217], off
	s_add_i32 m0, s55, 0x2000
	s_add_u32 s40, s40, 0x40080
	v_lshl_add_u64 v[216:217], v[218:219], 0, s[36:37]
	s_addc_u32 s41, s41, 0
	s_add_i32 s55, s57, s65
	global_load_lds_dwordx4 v[216:217], off
	v_lshl_add_u64 v[216:217], s[40:41], 0, v[0:1]
	s_mov_b32 m0, s55
	s_nop 0
	global_load_lds_dwordx4 v[216:217], off
	v_lshl_add_u64 v[216:217], s[40:41], 0, v[186:187]
	s_add_i32 m0, s55, 0x2000
	s_nop 0
	global_load_lds_dwordx4 v[216:217], off
	v_lshl_add_u64 v[216:217], v[236:237], 0, s[36:37]
	s_mov_b32 m0, s76
	s_nop 0
	global_load_lds_dwordx4 v[216:217], off
	v_lshl_add_u64 v[216:217], v[238:239], 0, s[36:37]
	s_mov_b32 m0, s77
	s_nop 0
	global_load_lds_dwordx4 v[216:217], off
	s_waitcnt vmcnt(8)
	s_waitcnt lgkmcnt(0)
	s_barrier
	s_setprio 1
	s_waitcnt lgkmcnt(0)
	v_mfma_f32_16x16x32_bf16 v[62:65], v[74:77], v[162:165], v[62:65]
	v_mfma_f32_16x16x32_bf16 v[58:61], v[82:85], v[162:165], v[58:61]
	v_mfma_f32_16x16x32_bf16 v[46:49], v[74:77], v[192:195], v[46:49]
	v_mfma_f32_16x16x32_bf16 v[42:45], v[82:85], v[192:195], v[42:45]
	v_mfma_f32_16x16x32_bf16 v[30:33], v[74:77], v[200:203], v[30:33]
	v_mfma_f32_16x16x32_bf16 v[26:29], v[82:85], v[200:203], v[26:29]
	v_mfma_f32_16x16x32_bf16 v[14:17], v[74:77], v[208:211], v[14:17]
	v_mfma_f32_16x16x32_bf16 v[10:13], v[82:85], v[208:211], v[10:13]
	v_mfma_f32_16x16x32_bf16 v[62:65], v[78:81], v[166:169], v[62:65]
	v_mfma_f32_16x16x32_bf16 v[58:61], v[90:93], v[166:169], v[58:61]
	v_mfma_f32_16x16x32_bf16 v[46:49], v[78:81], v[196:199], v[46:49]
	v_mfma_f32_16x16x32_bf16 v[42:45], v[90:93], v[196:199], v[42:45]
	v_mfma_f32_16x16x32_bf16 v[30:33], v[78:81], v[204:207], v[30:33]
	v_mfma_f32_16x16x32_bf16 v[26:29], v[90:93], v[204:207], v[26:29]
	v_mfma_f32_16x16x32_bf16 v[14:17], v[78:81], v[212:215], v[14:17]
	v_mfma_f32_16x16x32_bf16 v[10:13], v[90:93], v[212:215], v[10:13]
	s_setprio 2
	s_setprio 1
	v_mfma_f32_16x16x32_bf16 v[54:57], v[94:97], v[162:165], v[54:57]
	v_mfma_f32_16x16x32_bf16 v[50:53], v[102:105], v[162:165], v[50:53]
	v_mfma_f32_16x16x32_bf16 v[38:41], v[94:97], v[192:195], v[38:41]
	v_mfma_f32_16x16x32_bf16 v[34:37], v[102:105], v[192:195], v[34:37]
	v_mfma_f32_16x16x32_bf16 v[22:25], v[94:97], v[200:203], v[22:25]
	v_mfma_f32_16x16x32_bf16 v[18:21], v[102:105], v[200:203], v[18:21]
	v_mfma_f32_16x16x32_bf16 v[6:9], v[94:97], v[208:211], v[6:9]
	v_mfma_f32_16x16x32_bf16 v[2:5], v[102:105], v[208:211], v[2:5]
	v_mfma_f32_16x16x32_bf16 v[54:57], v[98:101], v[166:169], v[54:57]
	v_mfma_f32_16x16x32_bf16 v[50:53], v[110:113], v[166:169], v[50:53]
	v_mfma_f32_16x16x32_bf16 v[38:41], v[98:101], v[196:199], v[38:41]
	v_mfma_f32_16x16x32_bf16 v[34:37], v[110:113], v[196:199], v[34:37]
	v_mfma_f32_16x16x32_bf16 v[22:25], v[98:101], v[204:207], v[22:25]
	v_mfma_f32_16x16x32_bf16 v[18:21], v[110:113], v[204:207], v[18:21]
	v_mfma_f32_16x16x32_bf16 v[6:9], v[98:101], v[212:215], v[6:9]
	v_mfma_f32_16x16x32_bf16 v[2:5], v[110:113], v[212:215], v[2:5]
	s_setprio 2
	s_barrier
	s_add_i32 s49, s49, 2
	s_add_u32 s22, s22, 0x100
	s_addc_u32 s23, s23, 0
	s_add_u32 s45, s45, 0x100
	s_addc_u32 s47, s47, 0
	s_cmp_gt_u32 s49, 13
	s_cbranch_scc0 .LBB0_157

; #define PG8_STAGE(bufoff, gbase, voff) do { _Pragma("unroll") for (int _i = 0; _i < 2; ++_i) \
;         __builtin_amdgcn_global_load_lds((const unsigned*)((const char*)(gbase) + (voff)[_i]), (PG8_LAS unsigned*)(lds + (bufoff) + ldsw + _i * 8192), 16, 0, 0); } while (0)
; #define PG8_LDA(dst, b, h) do { _Pragma("unroll") for (int m = 0; m < 4; ++m) _Pragma("unroll") for (int k = 0; k < 2; ++k) dst[m][k] = *(const PG8_LAS bf16x8*)(lds + PG8_SA(b, h) + aoff + m * 2048 + k * 1024); } while (0)
; #define PG8_LDB(dst, b, h) do { _Pragma("unroll") for (int n = 0; n < 2; ++n) _Pragma("unroll") for (int k = 0; k < 2; ++k) dst[n][k] = *(const PG8_LAS bf16x8*)(lds + PG8_SB(b, h) + boff + n * 2048 + k * 1024); } while (0)
; #define PG8_MMA(ai, bj, At, Bt) do { __builtin_amdgcn_s_setprio(1); _Pragma("unroll") for (int m = 0; m < 4; ++m) _Pragma("unroll") for (int n = 0; n < 2; ++n) _Pragma("unroll") for (int k = 0; k < 2; ++k) \
;         acc[ai][bj][m][n] = __builtin_amdgcn_mfma_f32_16x16x32_bf16(Bt[n][k], At[m][k], acc[ai][bj][m][n], 0, 0, 0); __builtin_amdgcn_s_setprio(0); } while (0)
; #define PG8_WAIT_V(n) asm volatile("s_waitcnt vmcnt(" #n ")" ::: "memory")
; #define PG8_WAIT_L(n) asm volatile("s_waitcnt lgkmcnt(" #n ")" ::: "memory")
; #define PG8_BAR __builtin_amdgcn_s_barrier()
; #define PG8_SCHED __builtin_amdgcn_sched_barrier(0)
; template <class Epi, class Sched, bool ALIGN_EPI = false, bool SP2 = false>
; __device__ __forceinline__ void gemm_phase(PG8_LAS unsigned char* lds, const Gemm g, const Sched& S, const Epi& E) {
;     ...
;             PG8_LDB(B0, 0, 0); PG8_LDB(B1, 0, 1); PG8_SCHED; PG8_LDA(At, 0, 0); PG8_STAGE(PG8_SA(1, 1), a1 + hstep, voffA);
;             PG8_WAIT_V(8); PG8_WAIT_L(0); PG8_BAR; PG8_MMA(0, 0, At, B0); PG8_MMA(0, 1, At, B1); PG8_BAR; PG8_SCHED;
;             PG8_LDA(At, 0, 1); PG8_STAGE(PG8_SB(0, 0), b2, voffB); PG8_STAGE(PG8_SB(0, 1), b2 + hstep, voffB); PG8_STAGE(PG8_SA(0, 0), a2, voffA);
;             PG8_WAIT_V(8); PG8_WAIT_L(0); PG8_BAR; PG8_MMA(1, 0, At, B0); PG8_MMA(1, 1, At, B1); PG8_BAR; PG8_SCHED;
.Lpeel_p3:
	s_add_u32 s44, s42, 0xfffc0080
	s_addc_u32 s45, s43, -1
	s_add_i32 s62, 0, 0x10000
	s_cmp_eq_u32 s61, 12
	s_cselect_b32 s47, s15, s45
	s_cselect_b32 s46, s35, s44
	v_add_u32_e32 v144, s62, v148
	s_cselect_b32 s45, s13, s60
	s_cselect_b32 s44, s58, s59
	s_add_i32 s64, 0, 0x14000
	ds_read_b128 v[140:143], v144
	ds_read_b128 v[150:153], v144 offset:1024
	ds_read_b128 v[154:157], v144 offset:2048
	ds_read_b128 v[158:161], v144 offset:3072
	v_add_u32_e32 v144, s64, v148
	ds_read_b128 v[162:165], v144
	ds_read_b128 v[166:169], v144 offset:1024
	ds_read_b128 v[182:185], v144 offset:2048
	ds_read_b128 v[186:189], v144 offset:3072
	v_lshl_add_u64 v[144:145], s[42:43], 0, v[136:137]
	s_add_i32 m0, s49, 0xc000
	ds_read_b128 v[190:193], v149
	ds_read_b128 v[194:197], v149 offset:1024
	ds_read_b128 v[198:201], v149 offset:2048
	ds_read_b128 v[202:205], v149 offset:3072
	ds_read_b128 v[206:209], v149 offset:4096
	ds_read_b128 v[210:213], v149 offset:5120
	ds_read_b128 v[214:217], v149 offset:6144
	ds_read_b128 v[232:235], v149 offset:7168
	global_load_lds_dwordx4 v[144:145], off
	v_lshl_add_u64 v[144:145], s[42:43], 0, v[138:139]
	s_add_i32 m0, s49, 0xe000
	s_nop 0
	global_load_lds_dwordx4 v[144:145], off
	s_waitcnt lgkmcnt(0)
	s_barrier
	s_setprio 1
	s_waitcnt lgkmcnt(0)
	v_mfma_f32_16x16x32_bf16 v[126:129], v[140:143], v[190:193], v[126:129]
	v_mfma_f32_16x16x32_bf16 v[122:125], v[154:157], v[190:193], v[122:125]
	v_mfma_f32_16x16x32_bf16 v[110:113], v[140:143], v[198:201], v[110:113]
	v_mfma_f32_16x16x32_bf16 v[106:109], v[154:157], v[198:201], v[106:109]
	v_mfma_f32_16x16x32_bf16 v[94:97], v[140:143], v[206:209], v[94:97]
	v_mfma_f32_16x16x32_bf16 v[90:93], v[154:157], v[206:209], v[90:93]
	v_mfma_f32_16x16x32_bf16 v[78:81], v[140:143], v[214:217], v[78:81]
	v_mfma_f32_16x16x32_bf16 v[74:77], v[154:157], v[214:217], v[74:77]
	v_mfma_f32_16x16x32_bf16 v[126:129], v[150:153], v[194:197], v[126:129]
	v_mfma_f32_16x16x32_bf16 v[122:125], v[158:161], v[194:197], v[122:125]
	v_mfma_f32_16x16x32_bf16 v[110:113], v[150:153], v[202:205], v[110:113]
	v_mfma_f32_16x16x32_bf16 v[106:109], v[158:161], v[202:205], v[106:109]
	v_mfma_f32_16x16x32_bf16 v[94:97], v[150:153], v[210:213], v[94:97]
	v_mfma_f32_16x16x32_bf16 v[90:93], v[158:161], v[210:213], v[90:93]
	v_mfma_f32_16x16x32_bf16 v[78:81], v[150:153], v[232:235], v[78:81]
	v_mfma_f32_16x16x32_bf16 v[74:77], v[158:161], v[232:235], v[74:77]
	s_setprio 2
	s_setprio 1
	v_mfma_f32_16x16x32_bf16 v[118:121], v[162:165], v[190:193], v[118:121]
	v_mfma_f32_16x16x32_bf16 v[114:117], v[182:185], v[190:193], v[114:117]
	v_mfma_f32_16x16x32_bf16 v[102:105], v[162:165], v[198:201], v[102:105]
	v_mfma_f32_16x16x32_bf16 v[98:101], v[182:185], v[198:201], v[98:101]
	v_mfma_f32_16x16x32_bf16 v[86:89], v[162:165], v[206:209], v[86:89]
	v_mfma_f32_16x16x32_bf16 v[82:85], v[182:185], v[206:209], v[82:85]
	v_mfma_f32_16x16x32_bf16 v[70:73], v[162:165], v[214:217], v[70:73]
	v_mfma_f32_16x16x32_bf16 v[66:69], v[182:185], v[214:217], v[66:69]
	v_mfma_f32_16x16x32_bf16 v[118:121], v[166:169], v[194:197], v[118:121]
	v_mfma_f32_16x16x32_bf16 v[114:117], v[186:189], v[194:197], v[114:117]
	v_mfma_f32_16x16x32_bf16 v[102:105], v[166:169], v[202:205], v[102:105]
	v_mfma_f32_16x16x32_bf16 v[98:101], v[186:189], v[202:205], v[98:101]
	v_mfma_f32_16x16x32_bf16 v[86:89], v[166:169], v[210:213], v[86:89]
	v_mfma_f32_16x16x32_bf16 v[82:85], v[186:189], v[210:213], v[82:85]
	v_mfma_f32_16x16x32_bf16 v[70:73], v[166:169], v[232:235], v[70:73]
	v_mfma_f32_16x16x32_bf16 v[66:69], v[186:189], v[232:235], v[66:69]
	s_setprio 2
	s_barrier
	s_add_i32 s62, s62, s48
	v_lshl_add_u64 v[144:145], s[44:45], 0, v[0:1]
	s_mov_b32 m0, s62
	ds_read_b128 v[190:193], v149 offset:16384
	ds_read_b128 v[194:197], v149 offset:17408
	ds_read_b128 v[198:201], v149 offset:18432
	ds_read_b128 v[202:205], v149 offset:19456
	ds_read_b128 v[206:209], v149 offset:20480
	ds_read_b128 v[210:213], v149 offset:21504
	ds_read_b128 v[214:217], v149 offset:22528
	ds_read_b128 v[232:235], v149 offset:23552
	global_load_lds_dwordx4 v[144:145], off
	s_add_i32 m0, s62, 0x2000
	s_add_u32 s62, s44, 0x40000
	v_lshl_add_u64 v[218:219], s[44:45], 0, v[130:131]
	s_addc_u32 s63, s45, 0
	s_add_i32 s64, s64, s48
	global_load_lds_dwordx4 v[218:219], off
	v_lshl_add_u64 v[236:237], s[62:63], 0, v[0:1]
	s_mov_b32 m0, s64
	v_lshl_add_u64 v[238:239], s[46:47], 0, v[132:133]
	global_load_lds_dwordx4 v[236:237], off
	v_lshl_add_u64 v[236:237], s[62:63], 0, v[130:131]
	s_add_i32 m0, s64, 0x2000
	s_nop 0
	global_load_lds_dwordx4 v[236:237], off
	v_lshl_add_u64 v[236:237], s[46:47], 0, v[134:135]
	s_mov_b32 m0, s49
	s_nop 0
	global_load_lds_dwordx4 v[236:237], off
	s_mov_b32 m0, s50
	s_nop 0
	global_load_lds_dwordx4 v[238:239], off
	s_waitcnt lgkmcnt(0)
	s_barrier
; #define PG8_STAGE(bufoff, gbase, voff) do { _Pragma("unroll") for (int _i = 0; _i < 2; ++_i) \
;         __builtin_amdgcn_global_load_lds((const unsigned*)((const char*)(gbase) + (voff)[_i]), (PG8_LAS unsigned*)(lds + (bufoff) + ldsw + _i * 8192), 16, 0, 0); } while (0)
; #define PG8_LDA(dst, b, h) do { _Pragma("unroll") for (int m = 0; m < 4; ++m) _Pragma("unroll") for (int k = 0; k < 2; ++k) dst[m][k] = *(const PG8_LAS bf16x8*)(lds + PG8_SA(b, h) + aoff + m * 2048 + k * 1024); } while (0)
; #define PG8_LDB(dst, b, h) do { _Pragma("unroll") for (int n = 0; n < 2; ++n) _Pragma("unroll") for (int k = 0; k < 2; ++k) dst[n][k] = *(const PG8_LAS bf16x8*)(lds + PG8_SB(b, h) + boff + n * 2048 + k * 1024); } while (0)
; #define PG8_MMA(ai, bj, At, Bt) do { __builtin_amdgcn_s_setprio(1); _Pragma("unroll") for (int m = 0; m < 4; ++m) _Pragma("unroll") for (int n = 0; n < 2; ++n) _Pragma("unroll") for (int k = 0; k < 2; ++k) \
;         acc[ai][bj][m][n] = __builtin_amdgcn_mfma_f32_16x16x32_bf16(Bt[n][k], At[m][k], acc[ai][bj][m][n], 0, 0, 0); __builtin_amdgcn_s_setprio(0); } while (0)
; #define PG8_WAIT_V(n) asm volatile("s_waitcnt vmcnt(" #n ")" ::: "memory")
; #define PG8_WAIT_L(n) asm volatile("s_waitcnt lgkmcnt(" #n ")" ::: "memory")
; #define PG8_BAR __builtin_amdgcn_s_barrier()
; #define PG8_SCHED __builtin_amdgcn_sched_barrier(0)
; template <class Epi, class Sched, bool ALIGN_EPI = false, bool SP2 = false>
; __device__ __forceinline__ void gemm_phase(PG8_LAS unsigned char* lds, const Gemm g, const Sched& S, const Epi& E) {
;     ...
;             PG8_WAIT_V(8); PG8_WAIT_L(0); PG8_BAR; PG8_MMA(1, 0, At, B0); PG8_MMA(1, 1, At, B1); PG8_BAR; PG8_SCHED;
;             PG8_LDB(B0, 1, 0); PG8_LDB(B1, 1, 1); PG8_SCHED; PG8_LDA(At, 1, 0); PG8_STAGE(PG8_SA(0, 1), a2 + hstep, voffA);
;             PG8_WAIT_V(8); PG8_WAIT_L(0); PG8_BAR; PG8_MMA(0, 0, At, B0); PG8_MMA(0, 1, At, B1); PG8_BAR; PG8_SCHED;
	s_setprio 1
	s_waitcnt lgkmcnt(0)
	v_mfma_f32_16x16x32_bf16 v[62:65], v[140:143], v[190:193], v[62:65]
	v_mfma_f32_16x16x32_bf16 v[58:61], v[154:157], v[190:193], v[58:61]
	v_mfma_f32_16x16x32_bf16 v[46:49], v[140:143], v[198:201], v[46:49]
	v_mfma_f32_16x16x32_bf16 v[42:45], v[154:157], v[198:201], v[42:45]
	v_mfma_f32_16x16x32_bf16 v[30:33], v[140:143], v[206:209], v[30:33]
	v_mfma_f32_16x16x32_bf16 v[26:29], v[154:157], v[206:209], v[26:29]
	v_mfma_f32_16x16x32_bf16 v[14:17], v[140:143], v[214:217], v[14:17]
	v_mfma_f32_16x16x32_bf16 v[10:13], v[154:157], v[214:217], v[10:13]
	v_mfma_f32_16x16x32_bf16 v[62:65], v[150:153], v[194:197], v[62:65]
	v_mfma_f32_16x16x32_bf16 v[58:61], v[158:161], v[194:197], v[58:61]
	v_mfma_f32_16x16x32_bf16 v[46:49], v[150:153], v[202:205], v[46:49]
	v_mfma_f32_16x16x32_bf16 v[42:45], v[158:161], v[202:205], v[42:45]
	v_mfma_f32_16x16x32_bf16 v[30:33], v[150:153], v[210:213], v[30:33]
	v_mfma_f32_16x16x32_bf16 v[26:29], v[158:161], v[210:213], v[26:29]
	v_mfma_f32_16x16x32_bf16 v[14:17], v[150:153], v[232:235], v[14:17]
	v_mfma_f32_16x16x32_bf16 v[10:13], v[158:161], v[232:235], v[10:13]
	s_setprio 2
	s_setprio 1
	v_mfma_f32_16x16x32_bf16 v[54:57], v[162:165], v[190:193], v[54:57]
	v_mfma_f32_16x16x32_bf16 v[50:53], v[182:185], v[190:193], v[50:53]
	v_mfma_f32_16x16x32_bf16 v[38:41], v[162:165], v[198:201], v[38:41]
	v_mfma_f32_16x16x32_bf16 v[34:37], v[182:185], v[198:201], v[34:37]
	v_mfma_f32_16x16x32_bf16 v[22:25], v[162:165], v[206:209], v[22:25]
	v_mfma_f32_16x16x32_bf16 v[18:21], v[182:185], v[206:209], v[18:21]
	v_mfma_f32_16x16x32_bf16 v[6:9], v[162:165], v[214:217], v[6:9]
	v_mfma_f32_16x16x32_bf16 v[2:5], v[182:185], v[214:217], v[2:5]
	v_mfma_f32_16x16x32_bf16 v[54:57], v[166:169], v[194:197], v[54:57]
	v_mfma_f32_16x16x32_bf16 v[50:53], v[186:189], v[194:197], v[50:53]
	v_mfma_f32_16x16x32_bf16 v[38:41], v[166:169], v[202:205], v[38:41]
	v_mfma_f32_16x16x32_bf16 v[34:37], v[186:189], v[202:205], v[34:37]
	v_mfma_f32_16x16x32_bf16 v[22:25], v[166:169], v[210:213], v[22:25]
	v_mfma_f32_16x16x32_bf16 v[18:21], v[186:189], v[210:213], v[18:21]
	v_mfma_f32_16x16x32_bf16 v[6:9], v[166:169], v[232:235], v[6:9]
	v_mfma_f32_16x16x32_bf16 v[2:5], v[186:189], v[232:235], v[2:5]
	s_setprio 2
	s_barrier
	s_add_i32 s62, 0, 0x18000
	s_add_i32 s63, 0, 0x1c000
	v_add_u32_e32 v158, s62, v148
	v_add_u32_e32 v186, s63, v148
	ds_read_b128 v[140:143], v158
	ds_read_b128 v[150:153], v158 offset:1024
	ds_read_b128 v[154:157], v158 offset:2048
	ds_read_b128 v[158:161], v158 offset:3072
	ds_read_b128 v[162:165], v186
	ds_read_b128 v[166:169], v186 offset:1024
	ds_read_b128 v[182:185], v186 offset:2048
	ds_read_b128 v[186:189], v186 offset:3072
	s_add_u32 s46, s46, 0x40000
	s_addc_u32 s47, s47, 0
	s_mov_b32 m0, s51
	v_lshl_add_u64 v[240:241], s[46:47], 0, v[134:135]
	ds_read_b128 v[190:193], v149 offset:32768
	ds_read_b128 v[194:197], v149 offset:33792
	ds_read_b128 v[198:201], v149 offset:34816
	ds_read_b128 v[202:205], v149 offset:35840
	ds_read_b128 v[206:209], v149 offset:36864
	ds_read_b128 v[210:213], v149 offset:37888
	ds_read_b128 v[214:217], v149 offset:38912
	ds_read_b128 v[232:235], v149 offset:39936
	global_load_lds_dwordx4 v[240:241], off
	v_lshl_add_u64 v[240:241], s[46:47], 0, v[132:133]
	s_mov_b32 m0, s52
	s_nop 0
	global_load_lds_dwordx4 v[240:241], off
	s_waitcnt vmcnt(8)
	s_waitcnt lgkmcnt(0)
	s_barrier
	s_setprio 1
	s_waitcnt lgkmcnt(0)
	v_mfma_f32_16x16x32_bf16 v[126:129], v[140:143], v[190:193], v[126:129]
	v_mfma_f32_16x16x32_bf16 v[122:125], v[154:157], v[190:193], v[122:125]
	v_mfma_f32_16x16x32_bf16 v[110:113], v[140:143], v[198:201], v[110:113]
	v_mfma_f32_16x16x32_bf16 v[106:109], v[154:157], v[198:201], v[106:109]
	v_mfma_f32_16x16x32_bf16 v[94:97], v[140:143], v[206:209], v[94:97]
	v_mfma_f32_16x16x32_bf16 v[90:93], v[154:157], v[206:209], v[90:93]
	v_mfma_f32_16x16x32_bf16 v[78:81], v[140:143], v[214:217], v[78:81]
	v_mfma_f32_16x16x32_bf16 v[74:77], v[154:157], v[214:217], v[74:77]
	v_mfma_f32_16x16x32_bf16 v[126:129], v[150:153], v[194:197], v[126:129]
	v_mfma_f32_16x16x32_bf16 v[122:125], v[158:161], v[194:197], v[122:125]
	v_mfma_f32_16x16x32_bf16 v[110:113], v[150:153], v[202:205], v[110:113]
	v_mfma_f32_16x16x32_bf16 v[106:109], v[158:161], v[202:205], v[106:109]
	v_mfma_f32_16x16x32_bf16 v[94:97], v[150:153], v[210:213], v[94:97]
	v_mfma_f32_16x16x32_bf16 v[90:93], v[158:161], v[210:213], v[90:93]
	v_mfma_f32_16x16x32_bf16 v[78:81], v[150:153], v[232:235], v[78:81]
	v_mfma_f32_16x16x32_bf16 v[74:77], v[158:161], v[232:235], v[74:77]
	s_setprio 2
	s_setprio 1
	v_mfma_f32_16x16x32_bf16 v[118:121], v[162:165], v[190:193], v[118:121]
	v_mfma_f32_16x16x32_bf16 v[114:117], v[182:185], v[190:193], v[114:117]
	v_mfma_f32_16x16x32_bf16 v[102:105], v[162:165], v[198:201], v[102:105]
	v_mfma_f32_16x16x32_bf16 v[98:101], v[182:185], v[198:201], v[98:101]
	v_mfma_f32_16x16x32_bf16 v[86:89], v[162:165], v[206:209], v[86:89]
	v_mfma_f32_16x16x32_bf16 v[82:85], v[182:185], v[206:209], v[82:85]
	v_mfma_f32_16x16x32_bf16 v[70:73], v[162:165], v[214:217], v[70:73]
	v_mfma_f32_16x16x32_bf16 v[66:69], v[182:185], v[214:217], v[66:69]
	v_mfma_f32_16x16x32_bf16 v[118:121], v[166:169], v[194:197], v[118:121]
	v_mfma_f32_16x16x32_bf16 v[114:117], v[186:189], v[194:197], v[114:117]
	v_mfma_f32_16x16x32_bf16 v[102:105], v[166:169], v[202:205], v[102:105]
	v_mfma_f32_16x16x32_bf16 v[98:101], v[186:189], v[202:205], v[98:101]
	v_mfma_f32_16x16x32_bf16 v[86:89], v[166:169], v[210:213], v[86:89]
	v_mfma_f32_16x16x32_bf16 v[82:85], v[186:189], v[210:213], v[82:85]
	v_mfma_f32_16x16x32_bf16 v[70:73], v[166:169], v[232:235], v[70:73]
	v_mfma_f32_16x16x32_bf16 v[66:69], v[186:189], v[232:235], v[66:69]
	s_setprio 2
	s_barrier
; #define PG8_STAGE(bufoff, gbase, voff) do { _Pragma("unroll") for (int _i = 0; _i < 2; ++_i) \
;         __builtin_amdgcn_global_load_lds((const unsigned*)((const char*)(gbase) + (voff)[_i]), (PG8_LAS unsigned*)(lds + (bufoff) + ldsw + _i * 8192), 16, 0, 0); } while (0)
; #define PG8_LDA(dst, b, h) do { _Pragma("unroll") for (int m = 0; m < 4; ++m) _Pragma("unroll") for (int k = 0; k < 2; ++k) dst[m][k] = *(const PG8_LAS bf16x8*)(lds + PG8_SA(b, h) + aoff + m * 2048 + k * 1024); } while (0)
; #define PG8_LDB(dst, b, h) do { _Pragma("unroll") for (int n = 0; n < 2; ++n) _Pragma("unroll") for (int k = 0; k < 2; ++k) dst[n][k] = *(const PG8_LAS bf16x8*)(lds + PG8_SB(b, h) + boff + n * 2048 + k * 1024); } while (0)
; template <class Epi, class Sched, bool ALIGN_EPI = false, bool SP2 = false>
; __device__ __forceinline__ void gemm_phase(PG8_LAS unsigned char* lds, const Gemm g, const Sched& S, const Epi& E) {
;     ...
;         for (int t = 0; t < nt; t += 2) {
;             const bool last = (t == nt - 2);
;             const char* a1 = cA + (size_t)(t + 1) * kstep;
;             const char* a2 = last ? nA : cA + (size_t)(t + 2) * kstep; const char* b2 = last ? nB : cB + (size_t)(t + 2) * kstep;
;             const char* a3 = a2 + kstep; const char* b3 = b2 + kstep;
;             if (last && has_next) S.a_ready(nxt);
;             if constexpr (SP2) {
;             PG8_LDB(B0, 0, 0); PG8_LDB(B1, 0, 1); PG8_SCHED; PG8_LDA(At, 0, 0); PG8_STAGE(PG8_SA(1, 1), a1 + hstep, voffA);
;             PG8_WAIT_V(8); PG8_WAIT_L(0); PG8_BAR; PG8_MMA(0, 0, At, B0); PG8_MMA(0, 1, At, B1); PG8_BAR; PG8_SCHED;
;             PG8_LDA(At, 0, 1); PG8_STAGE(PG8_SB(0, 0), b2, voffB); PG8_STAGE(PG8_SB(0, 1), b2 + hstep, voffB); PG8_STAGE(PG8_SA(0, 0), a2, voffA);
;             PG8_WAIT_V(8); PG8_WAIT_L(0); PG8_BAR; PG8_MMA(1, 0, At, B0); PG8_MMA(1, 1, At, B1); PG8_BAR; PG8_SCHED;
;             PG8_LDB(B0, 1, 0); PG8_LDB(B1, 1, 1); PG8_SCHED; PG8_LDA(At, 1, 0); PG8_STAGE(PG8_SA(0, 1), a2 + hstep, voffA);
;             PG8_WAIT_V(8); PG8_WAIT_L(0); PG8_BAR; PG8_MMA(0, 0, At, B0); PG8_MMA(0, 1, At, B1); PG8_BAR; PG8_SCHED;
;             PG8_LDA(At, 1, 1); PG8_STAGE(PG8_SB(1, 0), b3, voffB); PG8_STAGE(PG8_SB(1, 1), b3 + hstep, voffB); PG8_STAGE(PG8_SA(1, 0), a3, voffA);
;             PG8_WAIT_V(8); PG8_WAIT_L(0); PG8_BAR; PG8_MMA(1, 0, At, B0); PG8_MMA(1, 1, At, B1); PG8_BAR; PG8_SCHED;
	s_add_i32 s46, s62, s48
	v_lshl_add_u64 v[144:145], v[144:145], 0, s[36:37]
	s_mov_b32 m0, s46
	ds_read_b128 v[190:193], v149 offset:49152
	ds_read_b128 v[194:197], v149 offset:50176
	ds_read_b128 v[198:201], v149 offset:51200
	ds_read_b128 v[202:205], v149 offset:52224
	ds_read_b128 v[206:209], v149 offset:53248
	ds_read_b128 v[210:213], v149 offset:54272
	ds_read_b128 v[214:217], v149 offset:55296
	ds_read_b128 v[232:235], v149 offset:56320
	global_load_lds_dwordx4 v[144:145], off
	s_add_i32 m0, s46, 0x2000
	s_add_u32 s44, s44, 0x40080
	v_lshl_add_u64 v[144:145], v[218:219], 0, s[36:37]
	s_addc_u32 s45, s45, 0
	s_add_i32 s46, s63, s48
	global_load_lds_dwordx4 v[144:145], off
	v_lshl_add_u64 v[144:145], s[44:45], 0, v[0:1]
	s_mov_b32 m0, s46
	s_nop 0
	global_load_lds_dwordx4 v[144:145], off
	v_lshl_add_u64 v[144:145], s[44:45], 0, v[130:131]
	s_add_i32 m0, s46, 0x2000
	s_nop 0
	global_load_lds_dwordx4 v[144:145], off
	v_lshl_add_u64 v[144:145], v[236:237], 0, s[36:37]
	s_mov_b32 m0, s54
	s_nop 0
	global_load_lds_dwordx4 v[144:145], off
	v_lshl_add_u64 v[144:145], v[238:239], 0, s[36:37]
	s_mov_b32 m0, s55
	s_nop 0
	global_load_lds_dwordx4 v[144:145], off
	s_waitcnt vmcnt(8)
	s_waitcnt lgkmcnt(0)
	s_barrier
	s_setprio 1
	s_waitcnt lgkmcnt(0)
	v_mfma_f32_16x16x32_bf16 v[62:65], v[140:143], v[190:193], v[62:65]
	v_mfma_f32_16x16x32_bf16 v[58:61], v[154:157], v[190:193], v[58:61]
	v_mfma_f32_16x16x32_bf16 v[46:49], v[140:143], v[198:201], v[46:49]
	v_mfma_f32_16x16x32_bf16 v[42:45], v[154:157], v[198:201], v[42:45]
	v_mfma_f32_16x16x32_bf16 v[30:33], v[140:143], v[206:209], v[30:33]
	v_mfma_f32_16x16x32_bf16 v[26:29], v[154:157], v[206:209], v[26:29]
	v_mfma_f32_16x16x32_bf16 v[14:17], v[140:143], v[214:217], v[14:17]
	v_mfma_f32_16x16x32_bf16 v[10:13], v[154:157], v[214:217], v[10:13]
	v_mfma_f32_16x16x32_bf16 v[62:65], v[150:153], v[194:197], v[62:65]
	v_mfma_f32_16x16x32_bf16 v[58:61], v[158:161], v[194:197], v[58:61]
	v_mfma_f32_16x16x32_bf16 v[46:49], v[150:153], v[202:205], v[46:49]
	v_mfma_f32_16x16x32_bf16 v[42:45], v[158:161], v[202:205], v[42:45]
	v_mfma_f32_16x16x32_bf16 v[30:33], v[150:153], v[210:213], v[30:33]
	v_mfma_f32_16x16x32_bf16 v[26:29], v[158:161], v[210:213], v[26:29]
	v_mfma_f32_16x16x32_bf16 v[14:17], v[150:153], v[232:235], v[14:17]
	v_mfma_f32_16x16x32_bf16 v[10:13], v[158:161], v[232:235], v[10:13]
	s_setprio 2
	s_setprio 1
	v_mfma_f32_16x16x32_bf16 v[54:57], v[162:165], v[190:193], v[54:57]
	v_mfma_f32_16x16x32_bf16 v[50:53], v[182:185], v[190:193], v[50:53]
	v_mfma_f32_16x16x32_bf16 v[38:41], v[162:165], v[198:201], v[38:41]
	v_mfma_f32_16x16x32_bf16 v[34:37], v[182:185], v[198:201], v[34:37]
	v_mfma_f32_16x16x32_bf16 v[22:25], v[162:165], v[206:209], v[22:25]
	v_mfma_f32_16x16x32_bf16 v[18:21], v[182:185], v[206:209], v[18:21]
	v_mfma_f32_16x16x32_bf16 v[6:9], v[162:165], v[214:217], v[6:9]
	v_mfma_f32_16x16x32_bf16 v[2:5], v[182:185], v[214:217], v[2:5]
	v_mfma_f32_16x16x32_bf16 v[54:57], v[166:169], v[194:197], v[54:57]
	v_mfma_f32_16x16x32_bf16 v[50:53], v[186:189], v[194:197], v[50:53]
	v_mfma_f32_16x16x32_bf16 v[38:41], v[166:169], v[202:205], v[38:41]
	v_mfma_f32_16x16x32_bf16 v[34:37], v[186:189], v[202:205], v[34:37]
	v_mfma_f32_16x16x32_bf16 v[22:25], v[166:169], v[210:213], v[22:25]
	v_mfma_f32_16x16x32_bf16 v[18:21], v[186:189], v[210:213], v[18:21]
	v_mfma_f32_16x16x32_bf16 v[6:9], v[166:169], v[232:235], v[6:9]
	v_mfma_f32_16x16x32_bf16 v[2:5], v[186:189], v[232:235], v[2:5]
	s_setprio 2
	s_barrier
	s_add_i32 s61, s61, 2
	s_add_u32 s42, s42, 0x100
	s_addc_u32 s43, s43, 0
	s_add_u32 s59, s59, 0x100
	s_addc_u32 s60, s60, 0
	s_cmp_gt_u32 s61, 13
	s_cbranch_scc0 .LBB0_985
	s_branch .Lafter_985
.LBB0_985:
	s_add_u32 s44, s42, 0xfffc0080
	s_addc_u32 s45, s43, -1
	s_add_i32 s62, 0, 0x10000
	s_cmp_eq_u32 s61, 12
	s_cselect_b32 s47, s15, s45
	s_cselect_b32 s46, s35, s44
	v_add_u32_e32 v144, s62, v148
	s_cselect_b32 s45, s13, s60
	s_cselect_b32 s44, s58, s59
	s_add_i32 s64, 0, 0x14000
	ds_read_b128 v[140:143], v144
	ds_read_b128 v[150:153], v144 offset:1024
	ds_read_b128 v[154:157], v144 offset:2048
	ds_read_b128 v[158:161], v144 offset:3072
	v_add_u32_e32 v144, s64, v148
	ds_read_b128 v[162:165], v144
	ds_read_b128 v[166:169], v144 offset:1024
	ds_read_b128 v[182:185], v144 offset:2048
	ds_read_b128 v[186:189], v144 offset:3072
	v_lshl_add_u64 v[144:145], s[42:43], 0, v[136:137]
	s_add_i32 m0, s49, 0xc000
	ds_read_b128 v[190:193], v149
	ds_read_b128 v[194:197], v149 offset:1024
	ds_read_b128 v[198:201], v149 offset:2048
	ds_read_b128 v[202:205], v149 offset:3072
	ds_read_b128 v[206:209], v149 offset:4096
	ds_read_b128 v[210:213], v149 offset:5120
	ds_read_b128 v[214:217], v149 offset:6144
	ds_read_b128 v[232:235], v149 offset:7168
	global_load_lds_dwordx4 v[144:145], off
	v_lshl_add_u64 v[144:145], s[42:43], 0, v[138:139]
	s_add_i32 m0, s49, 0xe000
	s_nop 0
	global_load_lds_dwordx4 v[144:145], off
	s_waitcnt vmcnt(8)
	s_waitcnt lgkmcnt(0)
	s_barrier
; #define PG8_STAGE(bufoff, gbase, voff) do { _Pragma("unroll") for (int _i = 0; _i < 2; ++_i) \
;         __builtin_amdgcn_global_load_lds((const unsigned*)((const char*)(gbase) + (voff)[_i]), (PG8_LAS unsigned*)(lds + (bufoff) + ldsw + _i * 8192), 16, 0, 0); } while (0)
; #define PG8_LDA(dst, b, h) do { _Pragma("unroll") for (int m = 0; m < 4; ++m) _Pragma("unroll") for (int k = 0; k < 2; ++k) dst[m][k] = *(const PG8_LAS bf16x8*)(lds + PG8_SA(b, h) + aoff + m * 2048 + k * 1024); } while (0)
; #define PG8_LDB(dst, b, h) do { _Pragma("unroll") for (int n = 0; n < 2; ++n) _Pragma("unroll") for (int k = 0; k < 2; ++k) dst[n][k] = *(const PG8_LAS bf16x8*)(lds + PG8_SB(b, h) + boff + n * 2048 + k * 1024); } while (0)
; #define PG8_MMA(ai, bj, At, Bt) do { __builtin_amdgcn_s_setprio(1); _Pragma("unroll") for (int m = 0; m < 4; ++m) _Pragma("unroll") for (int n = 0; n < 2; ++n) _Pragma("unroll") for (int k = 0; k < 2; ++k) \
;         acc[ai][bj][m][n] = __builtin_amdgcn_mfma_f32_16x16x32_bf16(Bt[n][k], At[m][k], acc[ai][bj][m][n], 0, 0, 0); __builtin_amdgcn_s_setprio(0); } while (0)
; #define PG8_WAIT_V(n) asm volatile("s_waitcnt vmcnt(" #n ")" ::: "memory")
; #define PG8_WAIT_L(n) asm volatile("s_waitcnt lgkmcnt(" #n ")" ::: "memory")
; #define PG8_BAR __builtin_amdgcn_s_barrier()
; #define PG8_SCHED __builtin_amdgcn_sched_barrier(0)
; template <class Epi, class Sched, bool ALIGN_EPI = false, bool SP2 = false>
; __device__ __forceinline__ void gemm_phase(PG8_LAS unsigned char* lds, const Gemm g, const Sched& S, const Epi& E) {
;     ...
;             PG8_LDB(B0, 0, 0); PG8_LDB(B1, 0, 1); PG8_SCHED; PG8_LDA(At, 0, 0); PG8_STAGE(PG8_SA(1, 1), a1 + hstep, voffA);
;             PG8_WAIT_V(8); PG8_WAIT_L(0); PG8_BAR; PG8_MMA(0, 0, At, B0); PG8_MMA(0, 1, At, B1); PG8_BAR; PG8_SCHED;
;             PG8_LDA(At, 0, 1); PG8_STAGE(PG8_SB(0, 0), b2, voffB); PG8_STAGE(PG8_SB(0, 1), b2 + hstep, voffB); PG8_STAGE(PG8_SA(0, 0), a2, voffA);
;             PG8_WAIT_V(8); PG8_WAIT_L(0); PG8_BAR; PG8_MMA(1, 0, At, B0); PG8_MMA(1, 1, At, B1); PG8_BAR; PG8_SCHED;
	s_setprio 1
	s_waitcnt lgkmcnt(0)
	v_mfma_f32_16x16x32_bf16 v[126:129], v[140:143], v[190:193], v[126:129]
	v_mfma_f32_16x16x32_bf16 v[122:125], v[154:157], v[190:193], v[122:125]
	v_mfma_f32_16x16x32_bf16 v[110:113], v[140:143], v[198:201], v[110:113]
	v_mfma_f32_16x16x32_bf16 v[106:109], v[154:157], v[198:201], v[106:109]
	v_mfma_f32_16x16x32_bf16 v[94:97], v[140:143], v[206:209], v[94:97]
	v_mfma_f32_16x16x32_bf16 v[90:93], v[154:157], v[206:209], v[90:93]
	v_mfma_f32_16x16x32_bf16 v[78:81], v[140:143], v[214:217], v[78:81]
	v_mfma_f32_16x16x32_bf16 v[74:77], v[154:157], v[214:217], v[74:77]
	v_mfma_f32_16x16x32_bf16 v[126:129], v[150:153], v[194:197], v[126:129]
	v_mfma_f32_16x16x32_bf16 v[122:125], v[158:161], v[194:197], v[122:125]
	v_mfma_f32_16x16x32_bf16 v[110:113], v[150:153], v[202:205], v[110:113]
	v_mfma_f32_16x16x32_bf16 v[106:109], v[158:161], v[202:205], v[106:109]
	v_mfma_f32_16x16x32_bf16 v[94:97], v[150:153], v[210:213], v[94:97]
	v_mfma_f32_16x16x32_bf16 v[90:93], v[158:161], v[210:213], v[90:93]
	v_mfma_f32_16x16x32_bf16 v[78:81], v[150:153], v[232:235], v[78:81]
	v_mfma_f32_16x16x32_bf16 v[74:77], v[158:161], v[232:235], v[74:77]
	s_setprio 2
	s_setprio 1
	v_mfma_f32_16x16x32_bf16 v[118:121], v[162:165], v[190:193], v[118:121]
	v_mfma_f32_16x16x32_bf16 v[114:117], v[182:185], v[190:193], v[114:117]
	v_mfma_f32_16x16x32_bf16 v[102:105], v[162:165], v[198:201], v[102:105]
	v_mfma_f32_16x16x32_bf16 v[98:101], v[182:185], v[198:201], v[98:101]
	v_mfma_f32_16x16x32_bf16 v[86:89], v[162:165], v[206:209], v[86:89]
	v_mfma_f32_16x16x32_bf16 v[82:85], v[182:185], v[206:209], v[82:85]
	v_mfma_f32_16x16x32_bf16 v[70:73], v[162:165], v[214:217], v[70:73]
	v_mfma_f32_16x16x32_bf16 v[66:69], v[182:185], v[214:217], v[66:69]
	v_mfma_f32_16x16x32_bf16 v[118:121], v[166:169], v[194:197], v[118:121]
	v_mfma_f32_16x16x32_bf16 v[114:117], v[186:189], v[194:197], v[114:117]
	v_mfma_f32_16x16x32_bf16 v[102:105], v[166:169], v[202:205], v[102:105]
	v_mfma_f32_16x16x32_bf16 v[98:101], v[186:189], v[202:205], v[98:101]
	v_mfma_f32_16x16x32_bf16 v[86:89], v[166:169], v[210:213], v[86:89]
	v_mfma_f32_16x16x32_bf16 v[82:85], v[186:189], v[210:213], v[82:85]
	v_mfma_f32_16x16x32_bf16 v[70:73], v[166:169], v[232:235], v[70:73]
	v_mfma_f32_16x16x32_bf16 v[66:69], v[186:189], v[232:235], v[66:69]
	s_setprio 2
	s_barrier
	s_add_i32 s62, s62, s48
	v_lshl_add_u64 v[144:145], s[44:45], 0, v[0:1]
	s_mov_b32 m0, s62
	ds_read_b128 v[190:193], v149 offset:16384
	ds_read_b128 v[194:197], v149 offset:17408
	ds_read_b128 v[198:201], v149 offset:18432
	ds_read_b128 v[202:205], v149 offset:19456
	ds_read_b128 v[206:209], v149 offset:20480
	ds_read_b128 v[210:213], v149 offset:21504
	ds_read_b128 v[214:217], v149 offset:22528
	ds_read_b128 v[232:235], v149 offset:23552
	global_load_lds_dwordx4 v[144:145], off
	s_add_i32 m0, s62, 0x2000
	s_add_u32 s62, s44, 0x40000
	v_lshl_add_u64 v[218:219], s[44:45], 0, v[130:131]
	s_addc_u32 s63, s45, 0
	s_add_i32 s64, s64, s48
	global_load_lds_dwordx4 v[218:219], off
	v_lshl_add_u64 v[236:237], s[62:63], 0, v[0:1]
	s_mov_b32 m0, s64
	v_lshl_add_u64 v[238:239], s[46:47], 0, v[132:133]
	global_load_lds_dwordx4 v[236:237], off
	v_lshl_add_u64 v[236:237], s[62:63], 0, v[130:131]
	s_add_i32 m0, s64, 0x2000
	s_nop 0
	global_load_lds_dwordx4 v[236:237], off
	v_lshl_add_u64 v[236:237], s[46:47], 0, v[134:135]
	s_mov_b32 m0, s49
	s_nop 0
	global_load_lds_dwordx4 v[236:237], off
	s_mov_b32 m0, s50
	s_nop 0
	global_load_lds_dwordx4 v[238:239], off
	s_waitcnt vmcnt(8)
	s_waitcnt lgkmcnt(0)
	s_barrier
	s_setprio 1
	s_waitcnt lgkmcnt(0)
	v_mfma_f32_16x16x32_bf16 v[62:65], v[140:143], v[190:193], v[62:65]
	v_mfma_f32_16x16x32_bf16 v[58:61], v[154:157], v[190:193], v[58:61]
	v_mfma_f32_16x16x32_bf16 v[46:49], v[140:143], v[198:201], v[46:49]
	v_mfma_f32_16x16x32_bf16 v[42:45], v[154:157], v[198:201], v[42:45]
	v_mfma_f32_16x16x32_bf16 v[30:33], v[140:143], v[206:209], v[30:33]
	v_mfma_f32_16x16x32_bf16 v[26:29], v[154:157], v[206:209], v[26:29]
	v_mfma_f32_16x16x32_bf16 v[14:17], v[140:143], v[214:217], v[14:17]
	v_mfma_f32_16x16x32_bf16 v[10:13], v[154:157], v[214:217], v[10:13]
	v_mfma_f32_16x16x32_bf16 v[62:65], v[150:153], v[194:197], v[62:65]
	v_mfma_f32_16x16x32_bf16 v[58:61], v[158:161], v[194:197], v[58:61]
	v_mfma_f32_16x16x32_bf16 v[46:49], v[150:153], v[202:205], v[46:49]
	v_mfma_f32_16x16x32_bf16 v[42:45], v[158:161], v[202:205], v[42:45]
	v_mfma_f32_16x16x32_bf16 v[30:33], v[150:153], v[210:213], v[30:33]
	v_mfma_f32_16x16x32_bf16 v[26:29], v[158:161], v[210:213], v[26:29]
	v_mfma_f32_16x16x32_bf16 v[14:17], v[150:153], v[232:235], v[14:17]
	v_mfma_f32_16x16x32_bf16 v[10:13], v[158:161], v[232:235], v[10:13]
	s_setprio 2
	s_setprio 1
	v_mfma_f32_16x16x32_bf16 v[54:57], v[162:165], v[190:193], v[54:57]
	v_mfma_f32_16x16x32_bf16 v[50:53], v[182:185], v[190:193], v[50:53]
	v_mfma_f32_16x16x32_bf16 v[38:41], v[162:165], v[198:201], v[38:41]
	v_mfma_f32_16x16x32_bf16 v[34:37], v[182:185], v[198:201], v[34:37]
	v_mfma_f32_16x16x32_bf16 v[22:25], v[162:165], v[206:209], v[22:25]
	v_mfma_f32_16x16x32_bf16 v[18:21], v[182:185], v[206:209], v[18:21]
	v_mfma_f32_16x16x32_bf16 v[6:9], v[162:165], v[214:217], v[6:9]
	v_mfma_f32_16x16x32_bf16 v[2:5], v[182:185], v[214:217], v[2:5]
	v_mfma_f32_16x16x32_bf16 v[54:57], v[166:169], v[194:197], v[54:57]
	v_mfma_f32_16x16x32_bf16 v[50:53], v[186:189], v[194:197], v[50:53]
	v_mfma_f32_16x16x32_bf16 v[38:41], v[166:169], v[202:205], v[38:41]
	v_mfma_f32_16x16x32_bf16 v[34:37], v[186:189], v[202:205], v[34:37]
	v_mfma_f32_16x16x32_bf16 v[22:25], v[166:169], v[210:213], v[22:25]
	v_mfma_f32_16x16x32_bf16 v[18:21], v[186:189], v[210:213], v[18:21]
	v_mfma_f32_16x16x32_bf16 v[6:9], v[166:169], v[232:235], v[6:9]
	v_mfma_f32_16x16x32_bf16 v[2:5], v[186:189], v[232:235], v[2:5]
	s_setprio 2
	s_barrier
; #define PG8_STAGE(bufoff, gbase, voff) do { _Pragma("unroll") for (int _i = 0; _i < 2; ++_i) \
;         __builtin_amdgcn_global_load_lds((const unsigned*)((const char*)(gbase) + (voff)[_i]), (PG8_LAS unsigned*)(lds + (bufoff) + ldsw + _i * 8192), 16, 0, 0); } while (0)
; #define PG8_LDA(dst, b, h) do { _Pragma("unroll") for (int m = 0; m < 4; ++m) _Pragma("unroll") for (int k = 0; k < 2; ++k) dst[m][k] = *(const PG8_LAS bf16x8*)(lds + PG8_SA(b, h) + aoff + m * 2048 + k * 1024); } while (0)
; #define PG8_LDB(dst, b, h) do { _Pragma("unroll") for (int n = 0; n < 2; ++n) _Pragma("unroll") for (int k = 0; k < 2; ++k) dst[n][k] = *(const PG8_LAS bf16x8*)(lds + PG8_SB(b, h) + boff + n * 2048 + k * 1024); } while (0)
; #define PG8_MMA(ai, bj, At, Bt) do { __builtin_amdgcn_s_setprio(1); _Pragma("unroll") for (int m = 0; m < 4; ++m) _Pragma("unroll") for (int n = 0; n < 2; ++n) _Pragma("unroll") for (int k = 0; k < 2; ++k) \
;         acc[ai][bj][m][n] = __builtin_amdgcn_mfma_f32_16x16x32_bf16(Bt[n][k], At[m][k], acc[ai][bj][m][n], 0, 0, 0); __builtin_amdgcn_s_setprio(0); } while (0)
; #define PG8_WAIT_V(n) asm volatile("s_waitcnt vmcnt(" #n ")" ::: "memory")
; #define PG8_WAIT_L(n) asm volatile("s_waitcnt lgkmcnt(" #n ")" ::: "memory")
; #define PG8_BAR __builtin_amdgcn_s_barrier()
; #define PG8_SCHED __builtin_amdgcn_sched_barrier(0)
; template <class Epi, class Sched, bool ALIGN_EPI = false, bool SP2 = false>
; __device__ __forceinline__ void gemm_phase(PG8_LAS unsigned char* lds, const Gemm g, const Sched& S, const Epi& E) {
;     ...
;             PG8_LDB(B0, 1, 0); PG8_LDB(B1, 1, 1); PG8_SCHED; PG8_LDA(At, 1, 0); PG8_STAGE(PG8_SA(0, 1), a2 + hstep, voffA);
;             PG8_WAIT_V(8); PG8_WAIT_L(0); PG8_BAR; PG8_MMA(0, 0, At, B0); PG8_MMA(0, 1, At, B1); PG8_BAR; PG8_SCHED;
	s_add_i32 s62, 0, 0x18000
	s_add_i32 s63, 0, 0x1c000
	v_add_u32_e32 v158, s62, v148
	v_add_u32_e32 v186, s63, v148
	ds_read_b128 v[140:143], v158
	ds_read_b128 v[150:153], v158 offset:1024
	ds_read_b128 v[154:157], v158 offset:2048
	ds_read_b128 v[158:161], v158 offset:3072
	ds_read_b128 v[162:165], v186
	ds_read_b128 v[166:169], v186 offset:1024
	ds_read_b128 v[182:185], v186 offset:2048
	ds_read_b128 v[186:189], v186 offset:3072
	s_add_u32 s46, s46, 0x40000
	s_addc_u32 s47, s47, 0
	s_mov_b32 m0, s51
	v_lshl_add_u64 v[240:241], s[46:47], 0, v[134:135]
	ds_read_b128 v[190:193], v149 offset:32768
	ds_read_b128 v[194:197], v149 offset:33792
	ds_read_b128 v[198:201], v149 offset:34816
	ds_read_b128 v[202:205], v149 offset:35840
	ds_read_b128 v[206:209], v149 offset:36864
	ds_read_b128 v[210:213], v149 offset:37888
	ds_read_b128 v[214:217], v149 offset:38912
	ds_read_b128 v[232:235], v149 offset:39936
	global_load_lds_dwordx4 v[240:241], off
	v_lshl_add_u64 v[240:241], s[46:47], 0, v[132:133]
	s_mov_b32 m0, s52
	s_nop 0
	global_load_lds_dwordx4 v[240:241], off
	s_waitcnt vmcnt(8)
	s_waitcnt lgkmcnt(0)
	s_barrier
	s_setprio 1
	s_waitcnt lgkmcnt(0)
	v_mfma_f32_16x16x32_bf16 v[126:129], v[140:143], v[190:193], v[126:129]
	v_mfma_f32_16x16x32_bf16 v[122:125], v[154:157], v[190:193], v[122:125]
	v_mfma_f32_16x16x32_bf16 v[110:113], v[140:143], v[198:201], v[110:113]
	v_mfma_f32_16x16x32_bf16 v[106:109], v[154:157], v[198:201], v[106:109]
	v_mfma_f32_16x16x32_bf16 v[94:97], v[140:143], v[206:209], v[94:97]
	v_mfma_f32_16x16x32_bf16 v[90:93], v[154:157], v[206:209], v[90:93]
	v_mfma_f32_16x16x32_bf16 v[78:81], v[140:143], v[214:217], v[78:81]
	v_mfma_f32_16x16x32_bf16 v[74:77], v[154:157], v[214:217], v[74:77]
	v_mfma_f32_16x16x32_bf16 v[126:129], v[150:153], v[194:197], v[126:129]
	v_mfma_f32_16x16x32_bf16 v[122:125], v[158:161], v[194:197], v[122:125]
	v_mfma_f32_16x16x32_bf16 v[110:113], v[150:153], v[202:205], v[110:113]
	v_mfma_f32_16x16x32_bf16 v[106:109], v[158:161], v[202:205], v[106:109]
	v_mfma_f32_16x16x32_bf16 v[94:97], v[150:153], v[210:213], v[94:97]
	v_mfma_f32_16x16x32_bf16 v[90:93], v[158:161], v[210:213], v[90:93]
	v_mfma_f32_16x16x32_bf16 v[78:81], v[150:153], v[232:235], v[78:81]
	v_mfma_f32_16x16x32_bf16 v[74:77], v[158:161], v[232:235], v[74:77]
	s_setprio 2
	s_setprio 1
	v_mfma_f32_16x16x32_bf16 v[118:121], v[162:165], v[190:193], v[118:121]
	v_mfma_f32_16x16x32_bf16 v[114:117], v[182:185], v[190:193], v[114:117]
	v_mfma_f32_16x16x32_bf16 v[102:105], v[162:165], v[198:201], v[102:105]
	v_mfma_f32_16x16x32_bf16 v[98:101], v[182:185], v[198:201], v[98:101]
	v_mfma_f32_16x16x32_bf16 v[86:89], v[162:165], v[206:209], v[86:89]
	v_mfma_f32_16x16x32_bf16 v[82:85], v[182:185], v[206:209], v[82:85]
	v_mfma_f32_16x16x32_bf16 v[70:73], v[162:165], v[214:217], v[70:73]
	v_mfma_f32_16x16x32_bf16 v[66:69], v[182:185], v[214:217], v[66:69]
	v_mfma_f32_16x16x32_bf16 v[118:121], v[166:169], v[194:197], v[118:121]
	v_mfma_f32_16x16x32_bf16 v[114:117], v[186:189], v[194:197], v[114:117]
	v_mfma_f32_16x16x32_bf16 v[102:105], v[166:169], v[202:205], v[102:105]
	v_mfma_f32_16x16x32_bf16 v[98:101], v[186:189], v[202:205], v[98:101]
	v_mfma_f32_16x16x32_bf16 v[86:89], v[166:169], v[210:213], v[86:89]
	v_mfma_f32_16x16x32_bf16 v[82:85], v[186:189], v[210:213], v[82:85]
	v_mfma_f32_16x16x32_bf16 v[70:73], v[166:169], v[232:235], v[70:73]
	v_mfma_f32_16x16x32_bf16 v[66:69], v[186:189], v[232:235], v[66:69]
	s_setprio 2
	s_barrier
; #define PG8_STAGE(bufoff, gbase, voff) do { _Pragma("unroll") for (int _i = 0; _i < 2; ++_i) \
;         __builtin_amdgcn_global_load_lds((const unsigned*)((const char*)(gbase) + (voff)[_i]), (PG8_LAS unsigned*)(lds + (bufoff) + ldsw + _i * 8192), 16, 0, 0); } while (0)
; #define PG8_LDA(dst, b, h) do { _Pragma("unroll") for (int m = 0; m < 4; ++m) _Pragma("unroll") for (int k = 0; k < 2; ++k) dst[m][k] = *(const PG8_LAS bf16x8*)(lds + PG8_SA(b, h) + aoff + m * 2048 + k * 1024); } while (0)
; #define PG8_LDB(dst, b, h) do { _Pragma("unroll") for (int n = 0; n < 2; ++n) _Pragma("unroll") for (int k = 0; k < 2; ++k) dst[n][k] = *(const PG8_LAS bf16x8*)(lds + PG8_SB(b, h) + boff + n * 2048 + k * 1024); } while (0)
; template <class Epi, class Sched, bool ALIGN_EPI = false, bool SP2 = false>
; __device__ __forceinline__ void gemm_phase(PG8_LAS unsigned char* lds, const Gemm g, const Sched& S, const Epi& E) {
;     ...
;         for (int t = 0; t < nt; t += 2) {
;             const bool last = (t == nt - 2);
;             const char* a1 = cA + (size_t)(t + 1) * kstep;
;             const char* a2 = last ? nA : cA + (size_t)(t + 2) * kstep; const char* b2 = last ? nB : cB + (size_t)(t + 2) * kstep;
;             const char* a3 = a2 + kstep; const char* b3 = b2 + kstep;
;             if (last && has_next) S.a_ready(nxt);
;             if constexpr (SP2) {
;             PG8_LDB(B0, 0, 0); PG8_LDB(B1, 0, 1); PG8_SCHED; PG8_LDA(At, 0, 0); PG8_STAGE(PG8_SA(1, 1), a1 + hstep, voffA);
;             PG8_WAIT_V(8); PG8_WAIT_L(0); PG8_BAR; PG8_MMA(0, 0, At, B0); PG8_MMA(0, 1, At, B1); PG8_BAR; PG8_SCHED;
;             PG8_LDA(At, 0, 1); PG8_STAGE(PG8_SB(0, 0), b2, voffB); PG8_STAGE(PG8_SB(0, 1), b2 + hstep, voffB); PG8_STAGE(PG8_SA(0, 0), a2, voffA);
;             PG8_WAIT_V(8); PG8_WAIT_L(0); PG8_BAR; PG8_MMA(1, 0, At, B0); PG8_MMA(1, 1, At, B1); PG8_BAR; PG8_SCHED;
;             PG8_LDB(B0, 1, 0); PG8_LDB(B1, 1, 1); PG8_SCHED; PG8_LDA(At, 1, 0); PG8_STAGE(PG8_SA(0, 1), a2 + hstep, voffA);
;             PG8_WAIT_V(8); PG8_WAIT_L(0); PG8_BAR; PG8_MMA(0, 0, At, B0); PG8_MMA(0, 1, At, B1); PG8_BAR; PG8_SCHED;
;             PG8_LDA(At, 1, 1); PG8_STAGE(PG8_SB(1, 0), b3, voffB); PG8_STAGE(PG8_SB(1, 1), b3 + hstep, voffB); PG8_STAGE(PG8_SA(1, 0), a3, voffA);
;             PG8_WAIT_V(8); PG8_WAIT_L(0); PG8_BAR; PG8_MMA(1, 0, At, B0); PG8_MMA(1, 1, At, B1); PG8_BAR; PG8_SCHED;
	s_add_i32 s46, s62, s48
	v_lshl_add_u64 v[144:145], v[144:145], 0, s[36:37]
	s_mov_b32 m0, s46
	ds_read_b128 v[190:193], v149 offset:49152
	ds_read_b128 v[194:197], v149 offset:50176
	ds_read_b128 v[198:201], v149 offset:51200
	ds_read_b128 v[202:205], v149 offset:52224
	ds_read_b128 v[206:209], v149 offset:53248
	ds_read_b128 v[210:213], v149 offset:54272
	ds_read_b128 v[214:217], v149 offset:55296
	ds_read_b128 v[232:235], v149 offset:56320
	global_load_lds_dwordx4 v[144:145], off
	s_add_i32 m0, s46, 0x2000
	s_add_u32 s44, s44, 0x40080
	v_lshl_add_u64 v[144:145], v[218:219], 0, s[36:37]
	s_addc_u32 s45, s45, 0
	s_add_i32 s46, s63, s48
	global_load_lds_dwordx4 v[144:145], off
	v_lshl_add_u64 v[144:145], s[44:45], 0, v[0:1]
	s_mov_b32 m0, s46
	s_nop 0
	global_load_lds_dwordx4 v[144:145], off
	v_lshl_add_u64 v[144:145], s[44:45], 0, v[130:131]
	s_add_i32 m0, s46, 0x2000
	s_nop 0
	global_load_lds_dwordx4 v[144:145], off
	v_lshl_add_u64 v[144:145], v[236:237], 0, s[36:37]
	s_mov_b32 m0, s54
	s_nop 0
	global_load_lds_dwordx4 v[144:145], off
	v_lshl_add_u64 v[144:145], v[238:239], 0, s[36:37]
	s_mov_b32 m0, s55
	s_nop 0
	global_load_lds_dwordx4 v[144:145], off
	s_waitcnt vmcnt(8)
	s_waitcnt lgkmcnt(0)
	s_barrier
	s_setprio 1
	s_waitcnt lgkmcnt(0)
	v_mfma_f32_16x16x32_bf16 v[62:65], v[140:143], v[190:193], v[62:65]
	v_mfma_f32_16x16x32_bf16 v[58:61], v[154:157], v[190:193], v[58:61]
	v_mfma_f32_16x16x32_bf16 v[46:49], v[140:143], v[198:201], v[46:49]
	v_mfma_f32_16x16x32_bf16 v[42:45], v[154:157], v[198:201], v[42:45]
	v_mfma_f32_16x16x32_bf16 v[30:33], v[140:143], v[206:209], v[30:33]
	v_mfma_f32_16x16x32_bf16 v[26:29], v[154:157], v[206:209], v[26:29]
	v_mfma_f32_16x16x32_bf16 v[14:17], v[140:143], v[214:217], v[14:17]
	v_mfma_f32_16x16x32_bf16 v[10:13], v[154:157], v[214:217], v[10:13]
	v_mfma_f32_16x16x32_bf16 v[62:65], v[150:153], v[194:197], v[62:65]
	v_mfma_f32_16x16x32_bf16 v[58:61], v[158:161], v[194:197], v[58:61]
	v_mfma_f32_16x16x32_bf16 v[46:49], v[150:153], v[202:205], v[46:49]
	v_mfma_f32_16x16x32_bf16 v[42:45], v[158:161], v[202:205], v[42:45]
	v_mfma_f32_16x16x32_bf16 v[30:33], v[150:153], v[210:213], v[30:33]
	v_mfma_f32_16x16x32_bf16 v[26:29], v[158:161], v[210:213], v[26:29]
	v_mfma_f32_16x16x32_bf16 v[14:17], v[150:153], v[232:235], v[14:17]
	v_mfma_f32_16x16x32_bf16 v[10:13], v[158:161], v[232:235], v[10:13]
	s_setprio 2
	s_setprio 1
	v_mfma_f32_16x16x32_bf16 v[54:57], v[162:165], v[190:193], v[54:57]
	v_mfma_f32_16x16x32_bf16 v[50:53], v[182:185], v[190:193], v[50:53]
	v_mfma_f32_16x16x32_bf16 v[38:41], v[162:165], v[198:201], v[38:41]
	v_mfma_f32_16x16x32_bf16 v[34:37], v[182:185], v[198:201], v[34:37]
	v_mfma_f32_16x16x32_bf16 v[22:25], v[162:165], v[206:209], v[22:25]
	v_mfma_f32_16x16x32_bf16 v[18:21], v[182:185], v[206:209], v[18:21]
	v_mfma_f32_16x16x32_bf16 v[6:9], v[162:165], v[214:217], v[6:9]
	v_mfma_f32_16x16x32_bf16 v[2:5], v[182:185], v[214:217], v[2:5]
	v_mfma_f32_16x16x32_bf16 v[54:57], v[166:169], v[194:197], v[54:57]
	v_mfma_f32_16x16x32_bf16 v[50:53], v[186:189], v[194:197], v[50:53]
	v_mfma_f32_16x16x32_bf16 v[38:41], v[166:169], v[202:205], v[38:41]
	v_mfma_f32_16x16x32_bf16 v[34:37], v[186:189], v[202:205], v[34:37]
	v_mfma_f32_16x16x32_bf16 v[22:25], v[166:169], v[210:213], v[22:25]
	v_mfma_f32_16x16x32_bf16 v[18:21], v[186:189], v[210:213], v[18:21]
	v_mfma_f32_16x16x32_bf16 v[6:9], v[166:169], v[232:235], v[6:9]
	v_mfma_f32_16x16x32_bf16 v[2:5], v[186:189], v[232:235], v[2:5]
	s_setprio 2
	s_barrier
	s_add_i32 s61, s61, 2
	s_add_u32 s42, s42, 0x100
	s_addc_u32 s43, s43, 0
	s_add_u32 s59, s59, 0x100
	s_addc_u32 s60, s60, 0
	s_cmp_gt_u32 s61, 13
	s_cbranch_scc0 .LBB0_985
